# epilogue operand loads of GLU/P4/P5/P7 with the default cache policy instead of nt (two load instructions touch each line; nt refetched it)
# speedup vs baseline: 1.0390x; 1.0112x over previous
.LBB0_616:
	v_lshl_add_u32 v146, s20, 8, v148
	v_lshl_or_b32 v144, s21, 7, v150
	v_ashrrev_i32_e32 v147, 31, v146
	v_ashrrev_i32_e32 v145, 31, v144
	v_lshlrev_b64 v[154:155], 13, v[146:147]
	v_lshl_add_u64 v[154:155], s[8:9], 0, v[154:155]
	v_lshlrev_b64 v[144:145], 1, v[144:145]
	v_lshl_add_u64 v[154:155], v[154:155], 0, v[144:145]
	global_load_dwordx4 v[154:157], v[154:155], off
	v_mul_f32_e32 v116, 0xbfb8aa3b, v116
	v_mul_f32_e32 v117, 0xbfb8aa3b, v117
	v_exp_f32_e32 v116, v116
	v_exp_f32_e32 v117, v117
	v_mul_f32_e32 v112, 0xbfb8aa3b, v112
	v_mul_f32_e32 v113, 0xbfb8aa3b, v113
	v_mul_f32_e32 v114, 0xbfb8aa3b, v114
	v_mul_f32_e32 v115, 0xbfb8aa3b, v115
	v_mul_f32_e32 v118, 0xbfb8aa3b, v118
	v_mul_f32_e32 v119, 0xbfb8aa3b, v119
	v_exp_f32_e32 v112, v112
	v_exp_f32_e32 v113, v113
	v_exp_f32_e32 v114, v114
	v_exp_f32_e32 v115, v115
	v_exp_f32_e32 v118, v118
	v_exp_f32_e32 v119, v119
	v_add_f32_e32 v116, 1.0, v116
	v_add_f32_e32 v117, 1.0, v117
	v_rcp_f32_e32 v116, v116
	v_rcp_f32_e32 v117, v117
	v_add_f32_e32 v112, 1.0, v112
	v_add_f32_e32 v113, 1.0, v113
	v_add_f32_e32 v114, 1.0, v114
	v_add_f32_e32 v115, 1.0, v115
	v_add_f32_e32 v118, 1.0, v118
	v_add_f32_e32 v119, 1.0, v119
	v_rcp_f32_e32 v112, v112
	v_rcp_f32_e32 v113, v113
	v_rcp_f32_e32 v114, v114
	v_rcp_f32_e32 v115, v115
	v_rcp_f32_e32 v118, v118
	v_rcp_f32_e32 v119, v119
	v_mul_f32_e32 v100, 0xbfb8aa3b, v100
	v_mul_f32_e32 v101, 0xbfb8aa3b, v101
	v_exp_f32_e32 v100, v100
	v_exp_f32_e32 v101, v101
	v_mul_f32_e32 v96, 0xbfb8aa3b, v96
	v_mul_f32_e32 v97, 0xbfb8aa3b, v97
	v_mul_f32_e32 v98, 0xbfb8aa3b, v98
	v_mul_f32_e32 v99, 0xbfb8aa3b, v99
	v_mul_f32_e32 v102, 0xbfb8aa3b, v102
	v_mul_f32_e32 v103, 0xbfb8aa3b, v103
	v_exp_f32_e32 v96, v96
	v_exp_f32_e32 v97, v97
	v_exp_f32_e32 v98, v98
	v_exp_f32_e32 v99, v99
	v_exp_f32_e32 v102, v102
	v_exp_f32_e32 v103, v103
	v_add_f32_e32 v100, 1.0, v100
	v_add_f32_e32 v101, 1.0, v101
	v_rcp_f32_e32 v100, v100
	v_rcp_f32_e32 v101, v101
	v_add_f32_e32 v96, 1.0, v96
	v_add_f32_e32 v97, 1.0, v97
	v_add_f32_e32 v98, 1.0, v98
	v_add_f32_e32 v99, 1.0, v99
	v_add_f32_e32 v102, 1.0, v102
	v_add_f32_e32 v103, 1.0, v103
	v_rcp_f32_e32 v96, v96
	v_rcp_f32_e32 v97, v97
	v_rcp_f32_e32 v98, v98
	v_rcp_f32_e32 v99, v99
	v_rcp_f32_e32 v102, v102
	v_rcp_f32_e32 v103, v103
	v_mul_f32_e32 v84, 0xbfb8aa3b, v84
	v_mul_f32_e32 v85, 0xbfb8aa3b, v85
	v_exp_f32_e32 v84, v84
	v_exp_f32_e32 v85, v85
	v_mul_f32_e32 v80, 0xbfb8aa3b, v80
	v_mul_f32_e32 v81, 0xbfb8aa3b, v81
	v_mul_f32_e32 v82, 0xbfb8aa3b, v82
	v_mul_f32_e32 v83, 0xbfb8aa3b, v83
	v_mul_f32_e32 v86, 0xbfb8aa3b, v86
	v_mul_f32_e32 v87, 0xbfb8aa3b, v87
	v_exp_f32_e32 v80, v80
	v_exp_f32_e32 v81, v81
	v_exp_f32_e32 v82, v82
	v_exp_f32_e32 v83, v83
	v_exp_f32_e32 v86, v86
	s_waitcnt vmcnt(0)
	v_lshlrev_b32_e32 v158, 16, v154
	v_and_b32_e32 v159, 0xffff0000, v154
	v_lshlrev_b32_e32 v160, 16, v156
	v_and_b32_e32 v161, 0xffff0000, v156
	v_lshlrev_b32_e32 v156, 16, v157
	v_and_b32_e32 v157, 0xffff0000, v157
	v_pk_mul_f32 v[124:125], v[124:125], v[158:159]
	v_lshlrev_b32_e32 v154, 16, v155
	v_and_b32_e32 v155, 0xffff0000, v155
	v_pk_mul_f32 v[116:117], v[116:117], v[124:125]
	v_pk_mul_f32 v[120:121], v[120:121], v[160:161]
	v_pk_mul_f32 v[122:123], v[122:123], v[156:157]
	v_pk_mul_f32 v[126:127], v[126:127], v[154:155]
	v_pk_mul_f32 v[122:123], v[114:115], v[122:123]
	v_pk_mul_f32 v[114:115], v[112:113], v[120:121]
	v_cvt_pk_bf16_f32 v112, v116, v117
	v_lshlrev_b64 v[116:117], 12, v[146:147]
	v_pk_mul_f32 v[118:119], v[118:119], v[126:127]
	v_lshl_add_u64 v[116:117], s[96:97], 0, v[116:117]
	v_cvt_pk_bf16_f32 v113, v118, v119
	v_cvt_pk_bf16_f32 v114, v114, v115
	v_cvt_pk_bf16_f32 v115, v122, v123
	v_lshl_add_u64 v[116:117], v[116:117], 0, v[144:145]
	global_store_dwordx4 v[116:117], v[112:115], off
	v_exp_f32_e32 v87, v87
	v_add_f32_e32 v84, 1.0, v84
	v_or_b32_e32 v112, 16, v146
	v_ashrrev_i32_e32 v113, 31, v112
	v_lshlrev_b64 v[114:115], 13, v[112:113]
	v_lshl_add_u64 v[114:115], s[8:9], 0, v[114:115]
	v_lshl_add_u64 v[114:115], v[114:115], 0, v[144:145]
	global_load_dwordx4 v[114:117], v[114:115], off
	v_add_f32_e32 v85, 1.0, v85
	v_rcp_f32_e32 v84, v84
	v_rcp_f32_e32 v85, v85
	v_add_f32_e32 v80, 1.0, v80
	v_add_f32_e32 v81, 1.0, v81
	v_add_f32_e32 v82, 1.0, v82
	v_add_f32_e32 v83, 1.0, v83
	v_add_f32_e32 v86, 1.0, v86
	v_add_f32_e32 v87, 1.0, v87
	v_rcp_f32_e32 v80, v80
	v_rcp_f32_e32 v81, v81
	v_rcp_f32_e32 v82, v82
	v_rcp_f32_e32 v83, v83
	v_rcp_f32_e32 v86, v86
	v_rcp_f32_e32 v87, v87
	v_mul_f32_e32 v68, 0xbfb8aa3b, v68
	v_mul_f32_e32 v69, 0xbfb8aa3b, v69
	v_exp_f32_e32 v68, v68
	v_exp_f32_e32 v69, v69
	v_mul_f32_e32 v64, 0xbfb8aa3b, v64
	v_mul_f32_e32 v65, 0xbfb8aa3b, v65
	v_mul_f32_e32 v66, 0xbfb8aa3b, v66
	v_mul_f32_e32 v67, 0xbfb8aa3b, v67
	v_mul_f32_e32 v70, 0xbfb8aa3b, v70
	v_mul_f32_e32 v71, 0xbfb8aa3b, v71
	v_exp_f32_e32 v64, v64
	v_exp_f32_e32 v65, v65
	v_exp_f32_e32 v66, v66
	v_exp_f32_e32 v67, v67
	v_exp_f32_e32 v70, v70
	v_exp_f32_e32 v71, v71
	v_add_f32_e32 v68, 1.0, v68
	v_add_f32_e32 v69, 1.0, v69
	v_rcp_f32_e32 v68, v68
	v_rcp_f32_e32 v69, v69
	v_add_f32_e32 v64, 1.0, v64
	v_add_f32_e32 v65, 1.0, v65
	v_add_f32_e32 v66, 1.0, v66
	v_add_f32_e32 v67, 1.0, v67
	v_add_f32_e32 v70, 1.0, v70
	v_add_f32_e32 v71, 1.0, v71
	v_rcp_f32_e32 v64, v64
	v_rcp_f32_e32 v65, v65
	v_rcp_f32_e32 v66, v66
	v_rcp_f32_e32 v67, v67
	v_rcp_f32_e32 v70, v70
	v_rcp_f32_e32 v71, v71
	v_mul_f32_e32 v52, 0xbfb8aa3b, v52
	v_mul_f32_e32 v53, 0xbfb8aa3b, v53
	v_exp_f32_e32 v52, v52
	v_exp_f32_e32 v53, v53
	v_mul_f32_e32 v48, 0xbfb8aa3b, v48
	v_mul_f32_e32 v49, 0xbfb8aa3b, v49
	v_mul_f32_e32 v50, 0xbfb8aa3b, v50
	v_mul_f32_e32 v51, 0xbfb8aa3b, v51
	v_mul_f32_e32 v54, 0xbfb8aa3b, v54
	v_mul_f32_e32 v55, 0xbfb8aa3b, v55
	v_exp_f32_e32 v48, v48
	v_exp_f32_e32 v49, v49
	v_exp_f32_e32 v50, v50
	v_exp_f32_e32 v51, v51
	v_exp_f32_e32 v54, v54
	v_exp_f32_e32 v55, v55
	v_add_f32_e32 v52, 1.0, v52
	v_add_f32_e32 v53, 1.0, v53
	v_rcp_f32_e32 v52, v52
	v_rcp_f32_e32 v53, v53
	v_add_f32_e32 v48, 1.0, v48
	v_add_f32_e32 v49, 1.0, v49
	v_add_f32_e32 v50, 1.0, v50
	v_add_f32_e32 v51, 1.0, v51
	v_add_f32_e32 v54, 1.0, v54
	v_add_f32_e32 v55, 1.0, v55
	v_rcp_f32_e32 v48, v48
	v_rcp_f32_e32 v49, v49
	v_rcp_f32_e32 v50, v50
	v_rcp_f32_e32 v51, v51
	v_rcp_f32_e32 v54, v54
	v_rcp_f32_e32 v55, v55
	s_waitcnt vmcnt(0)
	v_lshlrev_b32_e32 v118, 16, v114
	v_and_b32_e32 v119, 0xffff0000, v114
	v_lshlrev_b32_e32 v120, 16, v116
	v_and_b32_e32 v121, 0xffff0000, v116
	v_lshlrev_b32_e32 v116, 16, v117
	v_and_b32_e32 v117, 0xffff0000, v117
	v_pk_mul_f32 v[108:109], v[108:109], v[118:119]
	v_lshlrev_b32_e32 v114, 16, v115
	v_and_b32_e32 v115, 0xffff0000, v115
	v_pk_mul_f32 v[100:101], v[100:101], v[108:109]
	v_pk_mul_f32 v[104:105], v[104:105], v[120:121]
	v_pk_mul_f32 v[106:107], v[106:107], v[116:117]
	v_pk_mul_f32 v[110:111], v[110:111], v[114:115]
	v_pk_mul_f32 v[106:107], v[98:99], v[106:107]
	v_pk_mul_f32 v[98:99], v[96:97], v[104:105]
	v_cvt_pk_bf16_f32 v96, v100, v101
	v_lshlrev_b64 v[100:101], 12, v[112:113]
	v_pk_mul_f32 v[102:103], v[102:103], v[110:111]
	v_lshl_add_u64 v[100:101], s[96:97], 0, v[100:101]
	v_cvt_pk_bf16_f32 v97, v102, v103
	v_cvt_pk_bf16_f32 v98, v98, v99
	v_cvt_pk_bf16_f32 v99, v106, v107
	v_lshl_add_u64 v[100:101], v[100:101], 0, v[144:145]
	global_store_dwordx4 v[100:101], v[96:99], off
	v_mul_f32_e32 v36, 0xbfb8aa3b, v36
	v_mul_f32_e32 v37, 0xbfb8aa3b, v37
	v_or_b32_e32 v96, 32, v146
	v_ashrrev_i32_e32 v97, 31, v96
	v_lshlrev_b64 v[98:99], 13, v[96:97]
	v_lshl_add_u64 v[98:99], s[8:9], 0, v[98:99]
	v_lshl_add_u64 v[98:99], v[98:99], 0, v[144:145]
	global_load_dwordx4 v[98:101], v[98:99], off
	v_exp_f32_e32 v36, v36
	v_exp_f32_e32 v37, v37
	v_mul_f32_e32 v32, 0xbfb8aa3b, v32
	v_mul_f32_e32 v33, 0xbfb8aa3b, v33
	v_mul_f32_e32 v34, 0xbfb8aa3b, v34
	v_mul_f32_e32 v35, 0xbfb8aa3b, v35
	v_mul_f32_e32 v38, 0xbfb8aa3b, v38
	v_mul_f32_e32 v39, 0xbfb8aa3b, v39
	v_exp_f32_e32 v32, v32
	v_exp_f32_e32 v33, v33
	v_exp_f32_e32 v34, v34
	v_exp_f32_e32 v35, v35
	v_exp_f32_e32 v38, v38
	v_exp_f32_e32 v39, v39
	v_add_f32_e32 v36, 1.0, v36
	v_add_f32_e32 v37, 1.0, v37
	v_rcp_f32_e32 v36, v36
	v_rcp_f32_e32 v37, v37
	v_add_f32_e32 v32, 1.0, v32
	v_add_f32_e32 v33, 1.0, v33
	v_add_f32_e32 v34, 1.0, v34
	v_add_f32_e32 v35, 1.0, v35
	v_add_f32_e32 v38, 1.0, v38
	v_add_f32_e32 v39, 1.0, v39
	v_rcp_f32_e32 v32, v32
	v_rcp_f32_e32 v33, v33
	v_rcp_f32_e32 v34, v34
	v_rcp_f32_e32 v35, v35
	v_rcp_f32_e32 v38, v38
	v_rcp_f32_e32 v39, v39
	v_mul_f32_e32 v20, 0xbfb8aa3b, v20
	v_mul_f32_e32 v21, 0xbfb8aa3b, v21
	v_exp_f32_e32 v20, v20
	v_exp_f32_e32 v21, v21
	v_mul_f32_e32 v16, 0xbfb8aa3b, v16
	v_mul_f32_e32 v17, 0xbfb8aa3b, v17
	v_mul_f32_e32 v18, 0xbfb8aa3b, v18
	v_mul_f32_e32 v19, 0xbfb8aa3b, v19
	v_mul_f32_e32 v22, 0xbfb8aa3b, v22
	v_mul_f32_e32 v23, 0xbfb8aa3b, v23
	v_exp_f32_e32 v16, v16
	v_exp_f32_e32 v17, v17
	v_exp_f32_e32 v18, v18
	v_exp_f32_e32 v19, v19
	v_exp_f32_e32 v22, v22
	v_exp_f32_e32 v23, v23
	v_add_f32_e32 v20, 1.0, v20
	v_add_f32_e32 v21, 1.0, v21
	v_rcp_f32_e32 v20, v20
	v_rcp_f32_e32 v21, v21
	v_add_f32_e32 v16, 1.0, v16
	v_add_f32_e32 v17, 1.0, v17
	v_add_f32_e32 v18, 1.0, v18
	v_add_f32_e32 v19, 1.0, v19
	v_add_f32_e32 v22, 1.0, v22
	v_add_f32_e32 v23, 1.0, v23
	v_rcp_f32_e32 v16, v16
	v_rcp_f32_e32 v17, v17
	v_rcp_f32_e32 v18, v18
	v_rcp_f32_e32 v19, v19
	v_rcp_f32_e32 v22, v22
	v_rcp_f32_e32 v23, v23
	v_mul_f32_e32 v4, 0xbfb8aa3b, v4
	v_mul_f32_e32 v5, 0xbfb8aa3b, v5
	v_exp_f32_e32 v4, v4
	v_exp_f32_e32 v5, v5
	v_mul_f32_e32 v0, 0xbfb8aa3b, v0
	v_mul_f32_e32 v1, 0xbfb8aa3b, v1
	v_mul_f32_e32 v2, 0xbfb8aa3b, v2
	v_mul_f32_e32 v3, 0xbfb8aa3b, v3
	v_mul_f32_e32 v6, 0xbfb8aa3b, v6
	v_mul_f32_e32 v7, 0xbfb8aa3b, v7
	v_exp_f32_e32 v0, v0
	v_exp_f32_e32 v1, v1
	v_exp_f32_e32 v2, v2
	v_exp_f32_e32 v3, v3
	v_exp_f32_e32 v6, v6
	v_exp_f32_e32 v7, v7
	v_add_f32_e32 v4, 1.0, v4
	s_waitcnt vmcnt(0)
	v_lshlrev_b32_e32 v102, 16, v98
	v_and_b32_e32 v103, 0xffff0000, v98
	v_lshlrev_b32_e32 v104, 16, v100
	v_and_b32_e32 v105, 0xffff0000, v100
	v_lshlrev_b32_e32 v100, 16, v101
	v_and_b32_e32 v101, 0xffff0000, v101
	v_pk_mul_f32 v[92:93], v[92:93], v[102:103]
	v_lshlrev_b32_e32 v98, 16, v99
	v_and_b32_e32 v99, 0xffff0000, v99
	v_pk_mul_f32 v[84:85], v[84:85], v[92:93]
	v_pk_mul_f32 v[88:89], v[88:89], v[104:105]
	v_pk_mul_f32 v[90:91], v[90:91], v[100:101]
	v_pk_mul_f32 v[94:95], v[94:95], v[98:99]
	v_pk_mul_f32 v[90:91], v[82:83], v[90:91]
	v_pk_mul_f32 v[82:83], v[80:81], v[88:89]
	v_cvt_pk_bf16_f32 v80, v84, v85
	v_lshlrev_b64 v[84:85], 12, v[96:97]
	v_pk_mul_f32 v[86:87], v[86:87], v[94:95]
	v_lshl_add_u64 v[84:85], s[96:97], 0, v[84:85]
	v_cvt_pk_bf16_f32 v81, v86, v87
	v_cvt_pk_bf16_f32 v82, v82, v83
	v_cvt_pk_bf16_f32 v83, v90, v91
	v_lshl_add_u64 v[84:85], v[84:85], 0, v[144:145]
	global_store_dwordx4 v[84:85], v[80:83], off
	v_add_f32_e32 v5, 1.0, v5
	v_rcp_f32_e32 v4, v4
	v_or_b32_e32 v80, 48, v146
	v_ashrrev_i32_e32 v81, 31, v80
	v_lshlrev_b64 v[82:83], 13, v[80:81]
	v_lshl_add_u64 v[82:83], s[8:9], 0, v[82:83]
	v_lshl_add_u64 v[82:83], v[82:83], 0, v[144:145]
	global_load_dwordx4 v[82:85], v[82:83], off
	v_rcp_f32_e32 v5, v5
	v_add_f32_e32 v0, 1.0, v0
	v_add_f32_e32 v1, 1.0, v1
	v_add_f32_e32 v2, 1.0, v2
	v_add_f32_e32 v3, 1.0, v3
	v_add_f32_e32 v6, 1.0, v6
	v_add_f32_e32 v7, 1.0, v7
	v_rcp_f32_e32 v0, v0
	v_rcp_f32_e32 v1, v1
	v_rcp_f32_e32 v2, v2
	v_rcp_f32_e32 v3, v3
	v_rcp_f32_e32 v6, v6
	v_rcp_f32_e32 v7, v7
	s_mov_b64 s[20:21], -1
	s_andn2_b64 vcc, exec, s[38:39]
	s_waitcnt vmcnt(0)
	v_lshlrev_b32_e32 v86, 16, v82
	v_and_b32_e32 v87, 0xffff0000, v82
	v_lshlrev_b32_e32 v88, 16, v84
	v_and_b32_e32 v89, 0xffff0000, v84
	v_lshlrev_b32_e32 v84, 16, v85
	v_and_b32_e32 v85, 0xffff0000, v85
	v_pk_mul_f32 v[76:77], v[76:77], v[86:87]
	v_lshlrev_b32_e32 v82, 16, v83
	v_and_b32_e32 v83, 0xffff0000, v83
	v_pk_mul_f32 v[68:69], v[68:69], v[76:77]
	v_pk_mul_f32 v[72:73], v[72:73], v[88:89]
	v_pk_mul_f32 v[74:75], v[74:75], v[84:85]
	v_pk_mul_f32 v[78:79], v[78:79], v[82:83]
	v_pk_mul_f32 v[74:75], v[66:67], v[74:75]
	v_pk_mul_f32 v[66:67], v[64:65], v[72:73]
	v_cvt_pk_bf16_f32 v64, v68, v69
	v_lshlrev_b64 v[68:69], 12, v[80:81]
	v_pk_mul_f32 v[70:71], v[70:71], v[78:79]
	v_lshl_add_u64 v[68:69], s[96:97], 0, v[68:69]
	v_cvt_pk_bf16_f32 v65, v70, v71
	v_cvt_pk_bf16_f32 v66, v66, v67
	v_cvt_pk_bf16_f32 v67, v74, v75
	v_lshl_add_u64 v[68:69], v[68:69], 0, v[144:145]
	global_store_dwordx4 v[68:69], v[64:67], off
	s_nop 1
	v_add_u32_e32 v64, 0x80, v146
	v_ashrrev_i32_e32 v65, 31, v64
	v_lshlrev_b64 v[66:67], 13, v[64:65]
	v_lshl_add_u64 v[66:67], s[8:9], 0, v[66:67]
	v_lshl_add_u64 v[66:67], v[66:67], 0, v[144:145]
	global_load_dwordx4 v[66:69], v[66:67], off
	s_waitcnt vmcnt(0)
	v_lshlrev_b32_e32 v70, 16, v66
	v_and_b32_e32 v71, 0xffff0000, v66
	v_lshlrev_b32_e32 v72, 16, v68
	v_and_b32_e32 v73, 0xffff0000, v68
	v_lshlrev_b32_e32 v68, 16, v69
	v_and_b32_e32 v69, 0xffff0000, v69
	v_pk_mul_f32 v[60:61], v[60:61], v[70:71]
	v_lshlrev_b32_e32 v66, 16, v67
	v_and_b32_e32 v67, 0xffff0000, v67
	v_pk_mul_f32 v[52:53], v[52:53], v[60:61]
	v_pk_mul_f32 v[56:57], v[56:57], v[72:73]
	v_pk_mul_f32 v[58:59], v[58:59], v[68:69]
	v_pk_mul_f32 v[62:63], v[62:63], v[66:67]
	v_pk_mul_f32 v[58:59], v[50:51], v[58:59]
	v_pk_mul_f32 v[50:51], v[48:49], v[56:57]
	v_cvt_pk_bf16_f32 v48, v52, v53
	v_lshlrev_b64 v[52:53], 12, v[64:65]
	v_pk_mul_f32 v[54:55], v[54:55], v[62:63]
	v_lshl_add_u64 v[52:53], s[96:97], 0, v[52:53]
	v_cvt_pk_bf16_f32 v49, v54, v55
	v_cvt_pk_bf16_f32 v50, v50, v51
	v_cvt_pk_bf16_f32 v51, v58, v59
	v_lshl_add_u64 v[52:53], v[52:53], 0, v[144:145]
	global_store_dwordx4 v[52:53], v[48:51], off
	s_nop 1
	v_add_u32_e32 v48, 0x90, v146
	v_ashrrev_i32_e32 v49, 31, v48
	v_lshlrev_b64 v[50:51], 13, v[48:49]
	v_lshl_add_u64 v[50:51], s[8:9], 0, v[50:51]
	v_lshl_add_u64 v[50:51], v[50:51], 0, v[144:145]
	global_load_dwordx4 v[50:53], v[50:51], off
	s_waitcnt vmcnt(0)
	v_lshlrev_b32_e32 v54, 16, v50
	v_and_b32_e32 v55, 0xffff0000, v50
	v_lshlrev_b32_e32 v56, 16, v52
	v_and_b32_e32 v57, 0xffff0000, v52
	v_lshlrev_b32_e32 v52, 16, v53
	v_and_b32_e32 v53, 0xffff0000, v53
	v_pk_mul_f32 v[44:45], v[44:45], v[54:55]
	v_lshlrev_b32_e32 v50, 16, v51
	v_and_b32_e32 v51, 0xffff0000, v51
	v_pk_mul_f32 v[36:37], v[36:37], v[44:45]
	v_pk_mul_f32 v[40:41], v[40:41], v[56:57]
	v_pk_mul_f32 v[42:43], v[42:43], v[52:53]
	v_pk_mul_f32 v[46:47], v[46:47], v[50:51]
	v_pk_mul_f32 v[42:43], v[34:35], v[42:43]
	v_pk_mul_f32 v[34:35], v[32:33], v[40:41]
	v_cvt_pk_bf16_f32 v32, v36, v37
	v_lshlrev_b64 v[36:37], 12, v[48:49]
	v_pk_mul_f32 v[38:39], v[38:39], v[46:47]
	v_lshl_add_u64 v[36:37], s[96:97], 0, v[36:37]
	v_cvt_pk_bf16_f32 v33, v38, v39
	v_cvt_pk_bf16_f32 v34, v34, v35
	v_cvt_pk_bf16_f32 v35, v42, v43
	v_lshl_add_u64 v[36:37], v[36:37], 0, v[144:145]
	global_store_dwordx4 v[36:37], v[32:35], off
	s_nop 1
	v_add_u32_e32 v32, 0xa0, v146
	v_ashrrev_i32_e32 v33, 31, v32
	v_lshlrev_b64 v[34:35], 13, v[32:33]
	v_lshl_add_u64 v[34:35], s[8:9], 0, v[34:35]
	v_lshl_add_u64 v[34:35], v[34:35], 0, v[144:145]
	global_load_dwordx4 v[34:37], v[34:35], off
	s_waitcnt vmcnt(0)
	v_lshlrev_b32_e32 v38, 16, v34
	v_and_b32_e32 v39, 0xffff0000, v34
	v_lshlrev_b32_e32 v40, 16, v36
	v_and_b32_e32 v41, 0xffff0000, v36
	v_lshlrev_b32_e32 v36, 16, v37
	v_and_b32_e32 v37, 0xffff0000, v37
	v_pk_mul_f32 v[28:29], v[28:29], v[38:39]
	v_lshlrev_b32_e32 v34, 16, v35
	v_and_b32_e32 v35, 0xffff0000, v35
	v_pk_mul_f32 v[20:21], v[20:21], v[28:29]
	v_pk_mul_f32 v[24:25], v[24:25], v[40:41]
	v_pk_mul_f32 v[26:27], v[26:27], v[36:37]
	v_pk_mul_f32 v[30:31], v[30:31], v[34:35]
	v_pk_mul_f32 v[26:27], v[18:19], v[26:27]
	v_pk_mul_f32 v[18:19], v[16:17], v[24:25]
	v_cvt_pk_bf16_f32 v16, v20, v21
	v_lshlrev_b64 v[20:21], 12, v[32:33]
	v_pk_mul_f32 v[22:23], v[22:23], v[30:31]
	v_lshl_add_u64 v[20:21], s[96:97], 0, v[20:21]
	v_cvt_pk_bf16_f32 v17, v22, v23
	v_cvt_pk_bf16_f32 v18, v18, v19
	v_cvt_pk_bf16_f32 v19, v26, v27
	v_lshl_add_u64 v[20:21], v[20:21], 0, v[144:145]
	global_store_dwordx4 v[20:21], v[16:19], off
	s_nop 1
	v_add_u32_e32 v16, 0xb0, v146
	v_ashrrev_i32_e32 v17, 31, v16
	v_lshlrev_b64 v[18:19], 13, v[16:17]
	v_lshl_add_u64 v[18:19], s[8:9], 0, v[18:19]
	v_lshl_add_u64 v[18:19], v[18:19], 0, v[144:145]
	global_load_dwordx4 v[18:21], v[18:19], off
	s_waitcnt vmcnt(0)
	v_lshlrev_b32_e32 v22, 16, v18
	v_and_b32_e32 v23, 0xffff0000, v18
	v_lshlrev_b32_e32 v24, 16, v20
	v_and_b32_e32 v25, 0xffff0000, v20
	v_lshlrev_b32_e32 v20, 16, v21
	v_and_b32_e32 v21, 0xffff0000, v21
	v_pk_mul_f32 v[12:13], v[12:13], v[22:23]
	v_lshlrev_b32_e32 v18, 16, v19
	v_and_b32_e32 v19, 0xffff0000, v19
	v_pk_mul_f32 v[4:5], v[4:5], v[12:13]
	v_pk_mul_f32 v[8:9], v[8:9], v[24:25]
	v_pk_mul_f32 v[10:11], v[10:11], v[20:21]
	v_pk_mul_f32 v[14:15], v[14:15], v[18:19]
	v_pk_mul_f32 v[10:11], v[2:3], v[10:11]
	v_pk_mul_f32 v[2:3], v[0:1], v[8:9]
	v_cvt_pk_bf16_f32 v0, v4, v5
	v_lshlrev_b64 v[4:5], 12, v[16:17]
	v_pk_mul_f32 v[6:7], v[6:7], v[14:15]
	v_lshl_add_u64 v[4:5], s[96:97], 0, v[4:5]
	v_cvt_pk_bf16_f32 v1, v6, v7
	v_cvt_pk_bf16_f32 v2, v2, v3
	v_cvt_pk_bf16_f32 v3, v10, v11
	v_lshl_add_u64 v[4:5], v[4:5], 0, v[144:145]
	global_store_dwordx4 v[4:5], v[0:3], off
	s_cbranch_vccnz .LBB0_605
	s_andn2_b64 vcc, exec, s[0:1]
	s_cbranch_vccnz .LBB0_604
	s_barrier
	s_branch .LBB0_604

.LBB0_689:
	v_lshl_add_u32 v146, s10, 8, v148
	v_lshl_or_b32 v147, s11, 8, v150
	s_mov_b64 s[10:11], -1
	v_lshlrev_b32_e32 v147, 1, v147
	v_lshl_add_u32 v144, v146, 12, v147
	v_lshl_add_u32 v145, v146, 13, v147
	v_add_u32_e32 v145, 0x1000, v145
	v_mov_b32_e32 v160, v145
	global_load_dwordx4 v[160:163], v160, s[8:9]
	v_mov_b32_e32 v164, v144
	global_load_dwordx4 v[164:167], v164, s[96:97]
	v_mov_b32_e32 v168, v145
	global_load_dwordx4 v[168:171], v168, s[8:9] offset:256
	v_mov_b32_e32 v172, v144
	global_load_dwordx4 v[172:175], v172, s[96:97] offset:256
	v_add_u32_e32 v176, 0x20000, v145
	global_load_dwordx4 v[176:179], v176, s[8:9]
	v_add_u32_e32 v180, 0x10000, v144
	global_load_dwordx4 v[180:183], v180, s[96:97]
	v_add_u32_e32 v184, 0x20000, v145
	global_load_dwordx4 v[184:187], v184, s[8:9] offset:256
	v_add_u32_e32 v188, 0x10000, v144
	global_load_dwordx4 v[188:191], v188, s[96:97] offset:256
	v_add_u32_e32 v192, 0x40000, v145
	global_load_dwordx4 v[192:195], v192, s[8:9]
	v_add_u32_e32 v196, 0x20000, v144
	global_load_dwordx4 v[196:199], v196, s[96:97]
	v_add_u32_e32 v200, 0x40000, v145
	global_load_dwordx4 v[200:203], v200, s[8:9] offset:256
	v_add_u32_e32 v204, 0x20000, v144
	global_load_dwordx4 v[204:207], v204, s[96:97] offset:256
	v_add_u32_e32 v208, 0x60000, v145
	global_load_dwordx4 v[208:211], v208, s[8:9]
	v_add_u32_e32 v212, 0x30000, v144
	global_load_dwordx4 v[212:215], v212, s[96:97]
	v_add_u32_e32 v216, 0x60000, v145
	global_load_dwordx4 v[216:219], v216, s[8:9] offset:256
	v_add_u32_e32 v220, 0x30000, v144
	global_load_dwordx4 v[220:223], v220, s[96:97] offset:256
	s_waitcnt vmcnt(14)
	v_lshlrev_b32_e32 v146, 16, v161
	v_and_b32_e32 v147, 0xffff0000, v161
	v_and_b32_e32 v161, 0xffff0000, v160
	v_lshlrev_b32_e32 v160, 16, v160
	v_lshlrev_b32_e32 v154, 16, v163
	v_and_b32_e32 v155, 0xffff0000, v163
	v_and_b32_e32 v163, 0xffff0000, v162
	v_lshlrev_b32_e32 v162, 16, v162
	v_lshlrev_b32_e32 v156, 16, v165
	v_and_b32_e32 v157, 0xffff0000, v165
	v_and_b32_e32 v165, 0xffff0000, v164
	v_lshlrev_b32_e32 v164, 16, v164
	v_lshlrev_b32_e32 v158, 16, v167
	v_and_b32_e32 v159, 0xffff0000, v167
	v_and_b32_e32 v167, 0xffff0000, v166
	v_lshlrev_b32_e32 v166, 16, v166
	v_pk_fma_f32 v[124:125], v[124:125], v[160:161], v[164:165]
	v_pk_fma_f32 v[126:127], v[126:127], v[146:147], v[156:157]
	v_pk_fma_f32 v[120:121], v[120:121], v[162:163], v[166:167]
	v_pk_fma_f32 v[122:123], v[122:123], v[154:155], v[158:159]
	v_cvt_pk_bf16_f32 v124, v124, v125
	v_cvt_pk_bf16_f32 v125, v126, v127
	v_cvt_pk_bf16_f32 v126, v120, v121
	v_cvt_pk_bf16_f32 v127, v122, v123
	v_mov_b32_e32 v120, v144
	global_store_dwordx4 v120, v[124:127], s[16:17]
	v_add_u32_e32 v160, 0x100000, v145
	global_load_dwordx4 v[160:163], v160, s[8:9]
	v_add_u32_e32 v164, 0x80000, v144
	global_load_dwordx4 v[164:167], v164, s[96:97]
	s_waitcnt vmcnt(15)
	v_lshlrev_b32_e32 v146, 16, v169
	v_and_b32_e32 v147, 0xffff0000, v169
	v_and_b32_e32 v169, 0xffff0000, v168
	v_lshlrev_b32_e32 v168, 16, v168
	v_lshlrev_b32_e32 v154, 16, v171
	v_and_b32_e32 v155, 0xffff0000, v171
	v_and_b32_e32 v171, 0xffff0000, v170
	v_lshlrev_b32_e32 v170, 16, v170
	v_lshlrev_b32_e32 v156, 16, v173
	v_and_b32_e32 v157, 0xffff0000, v173
	v_and_b32_e32 v173, 0xffff0000, v172
	v_lshlrev_b32_e32 v172, 16, v172
	v_lshlrev_b32_e32 v158, 16, v175
	v_and_b32_e32 v159, 0xffff0000, v175
	v_and_b32_e32 v175, 0xffff0000, v174
	v_lshlrev_b32_e32 v174, 16, v174
	v_pk_fma_f32 v[116:117], v[116:117], v[168:169], v[172:173]
	v_pk_fma_f32 v[118:119], v[118:119], v[146:147], v[156:157]
	v_pk_fma_f32 v[112:113], v[112:113], v[170:171], v[174:175]
	v_pk_fma_f32 v[114:115], v[114:115], v[154:155], v[158:159]
	v_cvt_pk_bf16_f32 v116, v116, v117
	v_cvt_pk_bf16_f32 v117, v118, v119
	v_cvt_pk_bf16_f32 v118, v112, v113
	v_cvt_pk_bf16_f32 v119, v114, v115
	v_mov_b32_e32 v112, v144
	global_store_dwordx4 v112, v[116:119], s[16:17] offset:256
	v_add_u32_e32 v168, 0x100000, v145
	global_load_dwordx4 v[168:171], v168, s[8:9] offset:256
	v_add_u32_e32 v172, 0x80000, v144
	global_load_dwordx4 v[172:175], v172, s[96:97] offset:256
	s_waitcnt vmcnt(16)
	v_lshlrev_b32_e32 v146, 16, v177
	v_and_b32_e32 v147, 0xffff0000, v177
	v_and_b32_e32 v177, 0xffff0000, v176
	v_lshlrev_b32_e32 v176, 16, v176
	v_lshlrev_b32_e32 v154, 16, v179
	v_and_b32_e32 v155, 0xffff0000, v179
	v_and_b32_e32 v179, 0xffff0000, v178
	v_lshlrev_b32_e32 v178, 16, v178
	v_lshlrev_b32_e32 v156, 16, v181
	v_and_b32_e32 v157, 0xffff0000, v181
	v_and_b32_e32 v181, 0xffff0000, v180
	v_lshlrev_b32_e32 v180, 16, v180
	v_lshlrev_b32_e32 v158, 16, v183
	v_and_b32_e32 v159, 0xffff0000, v183
	v_and_b32_e32 v183, 0xffff0000, v182
	v_lshlrev_b32_e32 v182, 16, v182
	v_pk_fma_f32 v[108:109], v[108:109], v[176:177], v[180:181]
	v_pk_fma_f32 v[110:111], v[110:111], v[146:147], v[156:157]
	v_pk_fma_f32 v[104:105], v[104:105], v[178:179], v[182:183]
	v_pk_fma_f32 v[106:107], v[106:107], v[154:155], v[158:159]
	v_cvt_pk_bf16_f32 v108, v108, v109
	v_cvt_pk_bf16_f32 v109, v110, v111
	v_cvt_pk_bf16_f32 v110, v104, v105
	v_cvt_pk_bf16_f32 v111, v106, v107
	v_add_u32_e32 v104, 0x10000, v144
	global_store_dwordx4 v104, v[108:111], s[16:17]
	v_add_u32_e32 v176, 0x120000, v145
	global_load_dwordx4 v[176:179], v176, s[8:9]
	v_add_u32_e32 v180, 0x90000, v144
	global_load_dwordx4 v[180:183], v180, s[96:97]
	s_waitcnt vmcnt(17)
	v_lshlrev_b32_e32 v146, 16, v185
	v_and_b32_e32 v147, 0xffff0000, v185
	v_and_b32_e32 v185, 0xffff0000, v184
	v_lshlrev_b32_e32 v184, 16, v184
	v_lshlrev_b32_e32 v154, 16, v187
	v_and_b32_e32 v155, 0xffff0000, v187
	v_and_b32_e32 v187, 0xffff0000, v186
	v_lshlrev_b32_e32 v186, 16, v186
	v_lshlrev_b32_e32 v156, 16, v189
	v_and_b32_e32 v157, 0xffff0000, v189
	v_and_b32_e32 v189, 0xffff0000, v188
	v_lshlrev_b32_e32 v188, 16, v188
	v_lshlrev_b32_e32 v158, 16, v191
	v_and_b32_e32 v159, 0xffff0000, v191
	v_and_b32_e32 v191, 0xffff0000, v190
	v_lshlrev_b32_e32 v190, 16, v190
	v_pk_fma_f32 v[100:101], v[100:101], v[184:185], v[188:189]
	v_pk_fma_f32 v[102:103], v[102:103], v[146:147], v[156:157]
	v_pk_fma_f32 v[96:97], v[96:97], v[186:187], v[190:191]
	v_pk_fma_f32 v[98:99], v[98:99], v[154:155], v[158:159]
	v_cvt_pk_bf16_f32 v100, v100, v101
	v_cvt_pk_bf16_f32 v101, v102, v103
	v_cvt_pk_bf16_f32 v102, v96, v97
	v_cvt_pk_bf16_f32 v103, v98, v99
	v_add_u32_e32 v96, 0x10000, v144
	global_store_dwordx4 v96, v[100:103], s[16:17] offset:256
	v_add_u32_e32 v184, 0x120000, v145
	global_load_dwordx4 v[184:187], v184, s[8:9] offset:256
	v_add_u32_e32 v188, 0x90000, v144
	global_load_dwordx4 v[188:191], v188, s[96:97] offset:256
	s_waitcnt vmcnt(18)
	v_lshlrev_b32_e32 v146, 16, v193
	v_and_b32_e32 v147, 0xffff0000, v193
	v_and_b32_e32 v193, 0xffff0000, v192
	v_lshlrev_b32_e32 v192, 16, v192
	v_lshlrev_b32_e32 v154, 16, v195
	v_and_b32_e32 v155, 0xffff0000, v195
	v_and_b32_e32 v195, 0xffff0000, v194
	v_lshlrev_b32_e32 v194, 16, v194
	v_lshlrev_b32_e32 v156, 16, v197
	v_and_b32_e32 v157, 0xffff0000, v197
	v_and_b32_e32 v197, 0xffff0000, v196
	v_lshlrev_b32_e32 v196, 16, v196
	v_lshlrev_b32_e32 v158, 16, v199
	v_and_b32_e32 v159, 0xffff0000, v199
	v_and_b32_e32 v199, 0xffff0000, v198
	v_lshlrev_b32_e32 v198, 16, v198
	v_pk_fma_f32 v[92:93], v[92:93], v[192:193], v[196:197]
	v_pk_fma_f32 v[94:95], v[94:95], v[146:147], v[156:157]
	v_pk_fma_f32 v[88:89], v[88:89], v[194:195], v[198:199]
	v_pk_fma_f32 v[90:91], v[90:91], v[154:155], v[158:159]
	v_cvt_pk_bf16_f32 v92, v92, v93
	v_cvt_pk_bf16_f32 v93, v94, v95
	v_cvt_pk_bf16_f32 v94, v88, v89
	v_cvt_pk_bf16_f32 v95, v90, v91
	v_add_u32_e32 v88, 0x20000, v144
	global_store_dwordx4 v88, v[92:95], s[16:17]
	v_add_u32_e32 v192, 0x140000, v145
	global_load_dwordx4 v[192:195], v192, s[8:9]
	v_add_u32_e32 v196, 0xa0000, v144
	global_load_dwordx4 v[196:199], v196, s[96:97]
	s_waitcnt vmcnt(19)
	v_lshlrev_b32_e32 v146, 16, v201
	v_and_b32_e32 v147, 0xffff0000, v201
	v_and_b32_e32 v201, 0xffff0000, v200
	v_lshlrev_b32_e32 v200, 16, v200
	v_lshlrev_b32_e32 v154, 16, v203
	v_and_b32_e32 v155, 0xffff0000, v203
	v_and_b32_e32 v203, 0xffff0000, v202
	v_lshlrev_b32_e32 v202, 16, v202
	v_lshlrev_b32_e32 v156, 16, v205
	v_and_b32_e32 v157, 0xffff0000, v205
	v_and_b32_e32 v205, 0xffff0000, v204
	v_lshlrev_b32_e32 v204, 16, v204
	v_lshlrev_b32_e32 v158, 16, v207
	v_and_b32_e32 v159, 0xffff0000, v207
	v_and_b32_e32 v207, 0xffff0000, v206
	v_lshlrev_b32_e32 v206, 16, v206
	v_pk_fma_f32 v[84:85], v[84:85], v[200:201], v[204:205]
	v_pk_fma_f32 v[86:87], v[86:87], v[146:147], v[156:157]
	v_pk_fma_f32 v[80:81], v[80:81], v[202:203], v[206:207]
	v_pk_fma_f32 v[82:83], v[82:83], v[154:155], v[158:159]
	v_cvt_pk_bf16_f32 v84, v84, v85
	v_cvt_pk_bf16_f32 v85, v86, v87
	v_cvt_pk_bf16_f32 v86, v80, v81
	v_cvt_pk_bf16_f32 v87, v82, v83
	v_add_u32_e32 v80, 0x20000, v144
	global_store_dwordx4 v80, v[84:87], s[16:17] offset:256
	v_add_u32_e32 v200, 0x140000, v145
	global_load_dwordx4 v[200:203], v200, s[8:9] offset:256
	v_add_u32_e32 v204, 0xa0000, v144
	global_load_dwordx4 v[204:207], v204, s[96:97] offset:256
	s_waitcnt vmcnt(20)
	v_lshlrev_b32_e32 v146, 16, v209
	v_and_b32_e32 v147, 0xffff0000, v209
	v_and_b32_e32 v209, 0xffff0000, v208
	v_lshlrev_b32_e32 v208, 16, v208
	v_lshlrev_b32_e32 v154, 16, v211
	v_and_b32_e32 v155, 0xffff0000, v211
	v_and_b32_e32 v211, 0xffff0000, v210
	v_lshlrev_b32_e32 v210, 16, v210
	v_lshlrev_b32_e32 v156, 16, v213
	v_and_b32_e32 v157, 0xffff0000, v213
	v_and_b32_e32 v213, 0xffff0000, v212
	v_lshlrev_b32_e32 v212, 16, v212
	v_lshlrev_b32_e32 v158, 16, v215
	v_and_b32_e32 v159, 0xffff0000, v215
	v_and_b32_e32 v215, 0xffff0000, v214
	v_lshlrev_b32_e32 v214, 16, v214
	v_pk_fma_f32 v[76:77], v[76:77], v[208:209], v[212:213]
	v_pk_fma_f32 v[78:79], v[78:79], v[146:147], v[156:157]
	v_pk_fma_f32 v[72:73], v[72:73], v[210:211], v[214:215]
	v_pk_fma_f32 v[74:75], v[74:75], v[154:155], v[158:159]
	v_cvt_pk_bf16_f32 v76, v76, v77
	v_cvt_pk_bf16_f32 v77, v78, v79
	v_cvt_pk_bf16_f32 v78, v72, v73
	v_cvt_pk_bf16_f32 v79, v74, v75
	v_add_u32_e32 v72, 0x30000, v144
	global_store_dwordx4 v72, v[76:79], s[16:17]
	v_add_u32_e32 v208, 0x160000, v145
	global_load_dwordx4 v[208:211], v208, s[8:9]
	v_add_u32_e32 v212, 0xb0000, v144
	global_load_dwordx4 v[212:215], v212, s[96:97]
	s_waitcnt vmcnt(21)
	v_lshlrev_b32_e32 v146, 16, v217
	v_and_b32_e32 v147, 0xffff0000, v217
	v_and_b32_e32 v217, 0xffff0000, v216
	v_lshlrev_b32_e32 v216, 16, v216
	v_lshlrev_b32_e32 v154, 16, v219
	v_and_b32_e32 v155, 0xffff0000, v219
	v_and_b32_e32 v219, 0xffff0000, v218
	v_lshlrev_b32_e32 v218, 16, v218
	v_lshlrev_b32_e32 v156, 16, v221
	v_and_b32_e32 v157, 0xffff0000, v221
	v_and_b32_e32 v221, 0xffff0000, v220
	v_lshlrev_b32_e32 v220, 16, v220
	v_lshlrev_b32_e32 v158, 16, v223
	v_and_b32_e32 v159, 0xffff0000, v223
	v_and_b32_e32 v223, 0xffff0000, v222
	v_lshlrev_b32_e32 v222, 16, v222
	v_pk_fma_f32 v[68:69], v[68:69], v[216:217], v[220:221]
	v_pk_fma_f32 v[70:71], v[70:71], v[146:147], v[156:157]
	v_pk_fma_f32 v[64:65], v[64:65], v[218:219], v[222:223]
	v_pk_fma_f32 v[66:67], v[66:67], v[154:155], v[158:159]
	v_cvt_pk_bf16_f32 v68, v68, v69
	v_cvt_pk_bf16_f32 v69, v70, v71
	v_cvt_pk_bf16_f32 v70, v64, v65
	v_cvt_pk_bf16_f32 v71, v66, v67
	v_add_u32_e32 v64, 0x30000, v144
	global_store_dwordx4 v64, v[68:71], s[16:17] offset:256
	v_add_u32_e32 v216, 0x160000, v145
	global_load_dwordx4 v[216:219], v216, s[8:9] offset:256
	v_add_u32_e32 v220, 0xb0000, v144
	global_load_dwordx4 v[220:223], v220, s[96:97] offset:256
	s_waitcnt vmcnt(21)
	v_lshlrev_b32_e32 v146, 16, v161
	v_and_b32_e32 v147, 0xffff0000, v161
	v_and_b32_e32 v161, 0xffff0000, v160
	v_lshlrev_b32_e32 v160, 16, v160
	v_lshlrev_b32_e32 v154, 16, v163
	v_and_b32_e32 v155, 0xffff0000, v163
	v_and_b32_e32 v163, 0xffff0000, v162
	v_lshlrev_b32_e32 v162, 16, v162
	v_lshlrev_b32_e32 v156, 16, v165
	v_and_b32_e32 v157, 0xffff0000, v165
	v_and_b32_e32 v165, 0xffff0000, v164
	v_lshlrev_b32_e32 v164, 16, v164
	v_lshlrev_b32_e32 v158, 16, v167
	v_and_b32_e32 v159, 0xffff0000, v167
	v_and_b32_e32 v167, 0xffff0000, v166
	v_lshlrev_b32_e32 v166, 16, v166
	v_pk_fma_f32 v[60:61], v[60:61], v[160:161], v[164:165]
	v_pk_fma_f32 v[62:63], v[62:63], v[146:147], v[156:157]
	v_pk_fma_f32 v[56:57], v[56:57], v[162:163], v[166:167]
	v_pk_fma_f32 v[58:59], v[58:59], v[154:155], v[158:159]
	v_cvt_pk_bf16_f32 v60, v60, v61
	v_cvt_pk_bf16_f32 v61, v62, v63
	v_cvt_pk_bf16_f32 v62, v56, v57
	v_cvt_pk_bf16_f32 v63, v58, v59
	v_add_u32_e32 v56, 0x80000, v144
	global_store_dwordx4 v56, v[60:63], s[16:17]
	s_waitcnt vmcnt(19)
	v_lshlrev_b32_e32 v146, 16, v169
	v_and_b32_e32 v147, 0xffff0000, v169
	v_and_b32_e32 v169, 0xffff0000, v168
	v_lshlrev_b32_e32 v168, 16, v168
	v_lshlrev_b32_e32 v154, 16, v171
	v_and_b32_e32 v155, 0xffff0000, v171
	v_and_b32_e32 v171, 0xffff0000, v170
	v_lshlrev_b32_e32 v170, 16, v170
	v_lshlrev_b32_e32 v156, 16, v173
	v_and_b32_e32 v157, 0xffff0000, v173
	v_and_b32_e32 v173, 0xffff0000, v172
	v_lshlrev_b32_e32 v172, 16, v172
	v_lshlrev_b32_e32 v158, 16, v175
	v_and_b32_e32 v159, 0xffff0000, v175
	v_and_b32_e32 v175, 0xffff0000, v174
	v_lshlrev_b32_e32 v174, 16, v174
	v_pk_fma_f32 v[52:53], v[52:53], v[168:169], v[172:173]
	v_pk_fma_f32 v[54:55], v[54:55], v[146:147], v[156:157]
	v_pk_fma_f32 v[48:49], v[48:49], v[170:171], v[174:175]
	v_pk_fma_f32 v[50:51], v[50:51], v[154:155], v[158:159]
	v_cvt_pk_bf16_f32 v52, v52, v53
	v_cvt_pk_bf16_f32 v53, v54, v55
	v_cvt_pk_bf16_f32 v54, v48, v49
	v_cvt_pk_bf16_f32 v55, v50, v51
	v_add_u32_e32 v48, 0x80000, v144
	global_store_dwordx4 v48, v[52:55], s[16:17] offset:256
	s_waitcnt vmcnt(17)
	v_lshlrev_b32_e32 v146, 16, v177
	v_and_b32_e32 v147, 0xffff0000, v177
	v_and_b32_e32 v177, 0xffff0000, v176
	v_lshlrev_b32_e32 v176, 16, v176
	v_lshlrev_b32_e32 v154, 16, v179
	v_and_b32_e32 v155, 0xffff0000, v179
	v_and_b32_e32 v179, 0xffff0000, v178
	v_lshlrev_b32_e32 v178, 16, v178
	v_lshlrev_b32_e32 v156, 16, v181
	v_and_b32_e32 v157, 0xffff0000, v181
	v_and_b32_e32 v181, 0xffff0000, v180
	v_lshlrev_b32_e32 v180, 16, v180
	v_lshlrev_b32_e32 v158, 16, v183
	v_and_b32_e32 v159, 0xffff0000, v183
	v_and_b32_e32 v183, 0xffff0000, v182
	v_lshlrev_b32_e32 v182, 16, v182
	v_pk_fma_f32 v[44:45], v[44:45], v[176:177], v[180:181]
	v_pk_fma_f32 v[46:47], v[46:47], v[146:147], v[156:157]
	v_pk_fma_f32 v[40:41], v[40:41], v[178:179], v[182:183]
	v_pk_fma_f32 v[42:43], v[42:43], v[154:155], v[158:159]
	v_cvt_pk_bf16_f32 v44, v44, v45
	v_cvt_pk_bf16_f32 v45, v46, v47
	v_cvt_pk_bf16_f32 v46, v40, v41
	v_cvt_pk_bf16_f32 v47, v42, v43
	v_add_u32_e32 v40, 0x90000, v144
	global_store_dwordx4 v40, v[44:47], s[16:17]
	s_waitcnt vmcnt(15)
	v_lshlrev_b32_e32 v146, 16, v185
	v_and_b32_e32 v147, 0xffff0000, v185
	v_and_b32_e32 v185, 0xffff0000, v184
	v_lshlrev_b32_e32 v184, 16, v184
	v_lshlrev_b32_e32 v154, 16, v187
	v_and_b32_e32 v155, 0xffff0000, v187
	v_and_b32_e32 v187, 0xffff0000, v186
	v_lshlrev_b32_e32 v186, 16, v186
	v_lshlrev_b32_e32 v156, 16, v189
	v_and_b32_e32 v157, 0xffff0000, v189
	v_and_b32_e32 v189, 0xffff0000, v188
	v_lshlrev_b32_e32 v188, 16, v188
	v_lshlrev_b32_e32 v158, 16, v191
	v_and_b32_e32 v159, 0xffff0000, v191
	v_and_b32_e32 v191, 0xffff0000, v190
	v_lshlrev_b32_e32 v190, 16, v190
	v_pk_fma_f32 v[36:37], v[36:37], v[184:185], v[188:189]
	v_pk_fma_f32 v[38:39], v[38:39], v[146:147], v[156:157]
	v_pk_fma_f32 v[32:33], v[32:33], v[186:187], v[190:191]
	v_pk_fma_f32 v[34:35], v[34:35], v[154:155], v[158:159]
	v_cvt_pk_bf16_f32 v36, v36, v37
	v_cvt_pk_bf16_f32 v37, v38, v39
	v_cvt_pk_bf16_f32 v38, v32, v33
	v_cvt_pk_bf16_f32 v39, v34, v35
	v_add_u32_e32 v32, 0x90000, v144
	global_store_dwordx4 v32, v[36:39], s[16:17] offset:256
	s_waitcnt vmcnt(13)
	v_lshlrev_b32_e32 v146, 16, v193
	v_and_b32_e32 v147, 0xffff0000, v193
	v_and_b32_e32 v193, 0xffff0000, v192
	v_lshlrev_b32_e32 v192, 16, v192
	v_lshlrev_b32_e32 v154, 16, v195
	v_and_b32_e32 v155, 0xffff0000, v195
	v_and_b32_e32 v195, 0xffff0000, v194
	v_lshlrev_b32_e32 v194, 16, v194
	v_lshlrev_b32_e32 v156, 16, v197
	v_and_b32_e32 v157, 0xffff0000, v197
	v_and_b32_e32 v197, 0xffff0000, v196
	v_lshlrev_b32_e32 v196, 16, v196
	v_lshlrev_b32_e32 v158, 16, v199
	v_and_b32_e32 v159, 0xffff0000, v199
	v_and_b32_e32 v199, 0xffff0000, v198
	v_lshlrev_b32_e32 v198, 16, v198
	v_pk_fma_f32 v[28:29], v[28:29], v[192:193], v[196:197]
	v_pk_fma_f32 v[30:31], v[30:31], v[146:147], v[156:157]
	v_pk_fma_f32 v[24:25], v[24:25], v[194:195], v[198:199]
	v_pk_fma_f32 v[26:27], v[26:27], v[154:155], v[158:159]
	v_cvt_pk_bf16_f32 v28, v28, v29
	v_cvt_pk_bf16_f32 v29, v30, v31
	v_cvt_pk_bf16_f32 v30, v24, v25
	v_cvt_pk_bf16_f32 v31, v26, v27
	v_add_u32_e32 v24, 0xa0000, v144
	global_store_dwordx4 v24, v[28:31], s[16:17]
	s_waitcnt vmcnt(11)
	v_lshlrev_b32_e32 v146, 16, v201
	v_and_b32_e32 v147, 0xffff0000, v201
	v_and_b32_e32 v201, 0xffff0000, v200
	v_lshlrev_b32_e32 v200, 16, v200
	v_lshlrev_b32_e32 v154, 16, v203
	v_and_b32_e32 v155, 0xffff0000, v203
	v_and_b32_e32 v203, 0xffff0000, v202
	v_lshlrev_b32_e32 v202, 16, v202
	v_lshlrev_b32_e32 v156, 16, v205
	v_and_b32_e32 v157, 0xffff0000, v205
	v_and_b32_e32 v205, 0xffff0000, v204
	v_lshlrev_b32_e32 v204, 16, v204
	v_lshlrev_b32_e32 v158, 16, v207
	v_and_b32_e32 v159, 0xffff0000, v207
	v_and_b32_e32 v207, 0xffff0000, v206
	v_lshlrev_b32_e32 v206, 16, v206
	v_pk_fma_f32 v[20:21], v[20:21], v[200:201], v[204:205]
	v_pk_fma_f32 v[22:23], v[22:23], v[146:147], v[156:157]
	v_pk_fma_f32 v[16:17], v[16:17], v[202:203], v[206:207]
	v_pk_fma_f32 v[18:19], v[18:19], v[154:155], v[158:159]
	v_cvt_pk_bf16_f32 v20, v20, v21
	v_cvt_pk_bf16_f32 v21, v22, v23
	v_cvt_pk_bf16_f32 v22, v16, v17
	v_cvt_pk_bf16_f32 v23, v18, v19
	v_add_u32_e32 v16, 0xa0000, v144
	global_store_dwordx4 v16, v[20:23], s[16:17] offset:256
	s_waitcnt vmcnt(9)
	v_lshlrev_b32_e32 v146, 16, v209
	v_and_b32_e32 v147, 0xffff0000, v209
	v_and_b32_e32 v209, 0xffff0000, v208
	v_lshlrev_b32_e32 v208, 16, v208
	v_lshlrev_b32_e32 v154, 16, v211
	v_and_b32_e32 v155, 0xffff0000, v211
	v_and_b32_e32 v211, 0xffff0000, v210
	v_lshlrev_b32_e32 v210, 16, v210
	v_lshlrev_b32_e32 v156, 16, v213
	v_and_b32_e32 v157, 0xffff0000, v213
	v_and_b32_e32 v213, 0xffff0000, v212
	v_lshlrev_b32_e32 v212, 16, v212
	v_lshlrev_b32_e32 v158, 16, v215
	v_and_b32_e32 v159, 0xffff0000, v215
	v_and_b32_e32 v215, 0xffff0000, v214
	v_lshlrev_b32_e32 v214, 16, v214
	v_pk_fma_f32 v[12:13], v[12:13], v[208:209], v[212:213]
	v_pk_fma_f32 v[14:15], v[14:15], v[146:147], v[156:157]
	v_pk_fma_f32 v[8:9], v[8:9], v[210:211], v[214:215]
	v_pk_fma_f32 v[10:11], v[10:11], v[154:155], v[158:159]
	v_cvt_pk_bf16_f32 v12, v12, v13
	v_cvt_pk_bf16_f32 v13, v14, v15
	v_cvt_pk_bf16_f32 v14, v8, v9
	v_cvt_pk_bf16_f32 v15, v10, v11
	v_add_u32_e32 v8, 0xb0000, v144
	global_store_dwordx4 v8, v[12:15], s[16:17]
	s_waitcnt vmcnt(7)
	v_lshlrev_b32_e32 v146, 16, v217
	v_and_b32_e32 v147, 0xffff0000, v217
	v_and_b32_e32 v217, 0xffff0000, v216
	v_lshlrev_b32_e32 v216, 16, v216
	v_lshlrev_b32_e32 v154, 16, v219
	v_and_b32_e32 v155, 0xffff0000, v219
	v_and_b32_e32 v219, 0xffff0000, v218
	v_lshlrev_b32_e32 v218, 16, v218
	v_lshlrev_b32_e32 v156, 16, v221
	v_and_b32_e32 v157, 0xffff0000, v221
	v_and_b32_e32 v221, 0xffff0000, v220
	v_lshlrev_b32_e32 v220, 16, v220
	v_lshlrev_b32_e32 v158, 16, v223
	v_and_b32_e32 v159, 0xffff0000, v223
	v_and_b32_e32 v223, 0xffff0000, v222
	v_lshlrev_b32_e32 v222, 16, v222
	v_pk_fma_f32 v[4:5], v[4:5], v[216:217], v[220:221]
	v_pk_fma_f32 v[6:7], v[6:7], v[146:147], v[156:157]
	v_pk_fma_f32 v[0:1], v[0:1], v[218:219], v[222:223]
	v_pk_fma_f32 v[2:3], v[2:3], v[154:155], v[158:159]
	v_cvt_pk_bf16_f32 v4, v4, v5
	v_cvt_pk_bf16_f32 v5, v6, v7
	v_cvt_pk_bf16_f32 v6, v0, v1
	v_cvt_pk_bf16_f32 v7, v2, v3
	v_add_u32_e32 v0, 0xb0000, v144
	global_store_dwordx4 v0, v[4:7], s[16:17] offset:256
	s_andn2_b64 vcc, exec, s[38:39]
	s_cbranch_vccnz .LBB0_678
	s_andn2_b64 vcc, exec, s[18:19]
	s_cbranch_vccnz .LBB0_677
	s_barrier
	s_branch .LBB0_677

.LBB0_764:
	v_lshl_add_u32 v146, s30, 8, v150
	s_ashr_i32 s13, s30, 3
	s_mul_hi_i32 s23, s13, 0xc000
	s_mul_i32 s13, s13, 0xc000
	v_lshl_or_b32 v148, s28, 8, v152
	v_ashrrev_i32_e32 v147, 31, v146
	s_add_u32 s13, s64, s13
	v_lshlrev_b64 v[182:183], 11, v[146:147]
	v_ashrrev_i32_e32 v149, 31, v148
	v_readlane_b32 s68, v253, 24
	s_addc_u32 s23, s65, s23
	v_lshl_add_u64 v[184:185], v[182:183], 0, v[148:149]
	v_readlane_b32 s69, v253, 25
	s_add_u32 s30, s13, 0x4000
	v_lshlrev_b64 v[166:167], 2, v[184:185]
	s_mov_b64 s[52:53], s[68:69]
	s_addc_u32 s31, s23, 0
	v_lshlrev_b64 v[174:175], 2, v[148:149]
	v_lshl_add_u64 v[186:187], s[52:53], 0, v[166:167]
	v_lshl_add_u64 v[144:145], s[30:31], 0, v[174:175]
	global_load_dwordx4 v[158:161], v[186:187], off
	global_load_dwordx4 v[162:165], v[144:145], off
	v_lshl_add_u64 v[170:171], s[14:15], 0, v[166:167]
	s_add_u32 s28, s13, 0x8000
	v_readlane_b32 s82, v253, 38
	v_readlane_b32 s83, v253, 39
	s_addc_u32 s29, s23, 0
	s_mov_b64 s[66:67], s[82:83]
	v_lshl_add_u64 v[184:185], v[184:185], 1, s[20:21]
	v_readlane_b32 s70, v253, 26
	v_readlane_b32 s71, v253, 27
	v_readlane_b32 s72, v253, 28
	v_readlane_b32 s73, v253, 29
	v_readlane_b32 s74, v253, 30
	v_readlane_b32 s75, v253, 31
	v_readlane_b32 s76, v253, 32
	v_readlane_b32 s77, v253, 33
	v_readlane_b32 s78, v253, 34
	v_readlane_b32 s79, v253, 35
	v_readlane_b32 s80, v253, 36
	v_readlane_b32 s81, v253, 37
	s_waitcnt vmcnt(0)
	v_pk_fma_f32 v[160:161], v[126:127], v[164:165], v[160:161]
	v_pk_fma_f32 v[158:159], v[124:125], v[162:163], v[158:159]
	global_store_dwordx4 v[170:171], v[158:161], off
	global_load_dwordx4 v[162:165], v[144:145], off offset:16
	global_load_dwordx4 v[166:169], v[186:187], off offset:16
	v_lshl_add_u64 v[126:127], s[28:29], 0, v[174:175]
	v_or_b32_e32 v124, 0x80, v148
	v_ashrrev_i32_e32 v125, 31, v124
	v_lshlrev_b64 v[188:189], 2, v[124:125]
	v_lshl_add_u64 v[190:191], v[182:183], 0, v[124:125]
	s_waitcnt vmcnt(0)
	v_pk_fma_f32 v[164:165], v[122:123], v[164:165], v[168:169]
	v_pk_fma_f32 v[162:163], v[120:121], v[162:163], v[166:167]
	global_store_dwordx4 v[170:171], v[162:165], off offset:16
	global_load_dwordx4 v[166:169], v[126:127], off
	s_nop 0
	global_load_dwordx4 v[170:173], v[126:127], off offset:16
	v_lshl_add_u64 v[120:121], s[66:67], 0, v[174:175]
	global_load_dwordx4 v[174:177], v[120:121], off
	global_load_dwordx4 v[178:181], v[120:121], off offset:16
	v_lshl_add_u64 v[122:123], s[30:31], 0, v[188:189]
	s_waitcnt vmcnt(3)
	v_pk_add_f32 v[168:169], v[168:169], 1.0 op_sel_hi:[1,0]
	v_pk_add_f32 v[166:167], v[166:167], 1.0 op_sel_hi:[1,0]
	s_waitcnt vmcnt(2)
	v_pk_add_f32 v[172:173], v[172:173], 1.0 op_sel_hi:[1,0]
	v_pk_add_f32 v[170:171], v[170:171], 1.0 op_sel_hi:[1,0]
	s_waitcnt vmcnt(1)
	v_pk_mul_f32 v[168:169], v[176:177], v[168:169]
	v_pk_mul_f32 v[166:167], v[174:175], v[166:167]
	s_waitcnt vmcnt(0)
	v_pk_mul_f32 v[172:173], v[180:181], v[172:173]
	v_pk_mul_f32 v[170:171], v[178:179], v[170:171]
	v_pk_mul_f32 v[168:169], v[160:161], v[168:169]
	v_pk_mul_f32 v[166:167], v[158:159], v[166:167]
	v_pk_mul_f32 v[172:173], v[164:165], v[172:173]
	v_pk_mul_f32 v[170:171], v[162:163], v[170:171]
	v_cvt_pk_bf16_f32 v166, v166, v167
	v_cvt_pk_bf16_f32 v167, v168, v169
	v_cvt_pk_bf16_f32 v168, v170, v171
	v_cvt_pk_bf16_f32 v169, v172, v173
	global_store_dwordx4 v[184:185], v[166:169], off
	global_load_dwordx4 v[166:169], v[122:123], off
	s_nop 0
	global_load_dwordx4 v[170:173], v[186:187], off offset:512
	v_lshl_add_u64 v[178:179], v[190:191], 2, s[14:15]
	s_waitcnt vmcnt(0)
	v_pk_fma_f32 v[168:169], v[118:119], v[168:169], v[172:173]
	v_pk_fma_f32 v[166:167], v[116:117], v[166:167], v[170:171]
	global_store_dwordx4 v[178:179], v[166:169], off
	global_load_dwordx4 v[170:173], v[122:123], off offset:16
	global_load_dwordx4 v[174:177], v[186:187], off offset:528
	v_lshl_add_u64 v[116:117], s[28:29], 0, v[188:189]
	v_mul_f32_e32 v118, v165, v165
	v_fmac_f32_e32 v118, v164, v164
	s_waitcnt vmcnt(0)
	v_pk_fma_f32 v[172:173], v[114:115], v[172:173], v[176:177]
	v_pk_fma_f32 v[170:171], v[112:113], v[170:171], v[174:175]
	global_store_dwordx4 v[178:179], v[170:173], off offset:16
	global_load_dwordx4 v[174:177], v[116:117], off
	s_nop 0
	global_load_dwordx4 v[178:181], v[116:117], off offset:16
	global_load_dwordx4 v[182:185], v[120:121], off offset:512
	global_load_dwordx4 v[186:189], v[120:121], off offset:528
	v_and_b32_e32 v113, 64, v156
	v_xor_b32_e32 v112, 16, v156
	v_add_u32_e32 v113, 64, v113
	v_cmp_lt_i32_e32 vcc, v112, v113
	v_mul_f32_e32 v115, v161, v161
	v_fmac_f32_e32 v115, v160, v160
	v_cndmask_b32_e32 v112, v156, v112, vcc
	v_lshlrev_b32_e32 v114, 2, v112
	v_mul_f32_e32 v112, v159, v159
	v_fmac_f32_e32 v112, v158, v158
	v_add_f32_e32 v112, v112, v115
	v_mul_f32_e32 v115, v163, v163
	v_fmac_f32_e32 v115, v162, v162
	v_add_f32_e32 v115, v115, v118
	v_add_f32_e32 v112, v112, v115
	v_mul_f32_e32 v115, v167, v167
	v_mul_f32_e32 v118, v169, v169
	v_fmac_f32_e32 v115, v166, v166
	v_fmac_f32_e32 v118, v168, v168
	v_add_f32_e32 v115, v115, v118
	v_add_f32_e32 v112, v112, v115
	v_mul_f32_e32 v115, v171, v171
	v_mul_f32_e32 v118, v173, v173
	v_fmac_f32_e32 v115, v170, v170
	v_fmac_f32_e32 v118, v172, v172
	v_add_f32_e32 v115, v115, v118
	v_add_f32_e32 v112, v112, v115
	ds_bpermute_b32 v118, v114, v112
	v_xor_b32_e32 v115, 32, v156
	v_cmp_lt_i32_e32 vcc, v115, v113
	s_waitcnt lgkmcnt(0)
	v_add_f32_e32 v112, v112, v118
	v_cndmask_b32_e32 v113, v156, v115, vcc
	v_lshlrev_b32_e32 v115, 2, v113
	ds_bpermute_b32 v113, v115, v112
	s_waitcnt vmcnt(3)
	v_pk_add_f32 v[118:119], v[176:177], 1.0 op_sel_hi:[1,0]
	v_pk_add_f32 v[158:159], v[174:175], 1.0 op_sel_hi:[1,0]
	s_waitcnt vmcnt(2)
	v_pk_add_f32 v[160:161], v[180:181], 1.0 op_sel_hi:[1,0]
	v_pk_add_f32 v[162:163], v[178:179], 1.0 op_sel_hi:[1,0]
	s_waitcnt vmcnt(1)
	v_pk_mul_f32 v[118:119], v[184:185], v[118:119]
	v_pk_mul_f32 v[158:159], v[182:183], v[158:159]
	s_waitcnt vmcnt(0)
	v_pk_mul_f32 v[160:161], v[188:189], v[160:161]
	v_pk_mul_f32 v[162:163], v[186:187], v[162:163]
	v_pk_mul_f32 v[118:119], v[168:169], v[118:119]
	v_pk_mul_f32 v[158:159], v[166:167], v[158:159]
	v_pk_mul_f32 v[164:165], v[172:173], v[160:161]
	v_pk_mul_f32 v[160:161], v[170:171], v[162:163]
	v_cvt_pk_bf16_f32 v158, v158, v159
	v_cvt_pk_bf16_f32 v159, v118, v119
	v_cvt_pk_bf16_f32 v160, v160, v161
	v_cvt_pk_bf16_f32 v161, v164, v165
	v_lshl_add_u64 v[118:119], v[190:191], 1, s[20:21]
	global_store_dwordx4 v[118:119], v[158:161], off
	s_and_saveexec_b64 s[28:29], s[0:1]
	s_cbranch_execz .LBB0_766
	v_lshl_add_u64 v[118:119], v[146:147], 2, s[18:19]
	s_waitcnt lgkmcnt(0)
	v_add_f32_e32 v112, v112, v113
	global_atomic_add_f32 v[118:119], v112, off
.LBB0_766:
	s_or_b64 exec, exec, s[28:29]
	v_or_b32_e32 v112, 16, v146
	s_waitcnt lgkmcnt(0)
	v_ashrrev_i32_e32 v113, 31, v112
	v_lshlrev_b64 v[118:119], 11, v[112:113]
	v_lshl_add_u64 v[174:175], v[118:119], 0, v[148:149]
	v_readlane_b32 s68, v253, 24
	v_lshlrev_b64 v[166:167], 2, v[174:175]
	v_readlane_b32 s69, v253, 25
	global_load_dwordx4 v[158:161], v[144:145], off
	v_lshl_add_u64 v[174:175], v[174:175], 1, s[20:21]
	v_lshl_add_u64 v[176:177], s[68:69], 0, v[166:167]
	global_load_dwordx4 v[162:165], v[176:177], off
	v_lshl_add_u64 v[166:167], s[14:15], 0, v[166:167]
	v_lshl_add_u64 v[118:119], v[118:119], 0, v[124:125]
	v_readlane_b32 s70, v253, 26
	v_readlane_b32 s71, v253, 27
	v_readlane_b32 s72, v253, 28
	v_readlane_b32 s73, v253, 29
	v_readlane_b32 s74, v253, 30
	v_readlane_b32 s75, v253, 31
	v_readlane_b32 s76, v253, 32
	v_readlane_b32 s77, v253, 33
	v_readlane_b32 s78, v253, 34
	v_readlane_b32 s79, v253, 35
	v_readlane_b32 s80, v253, 36
	v_readlane_b32 s81, v253, 37
	v_readlane_b32 s82, v253, 38
	v_readlane_b32 s83, v253, 39
	s_waitcnt vmcnt(0)
	v_pk_fma_f32 v[110:111], v[110:111], v[160:161], v[164:165]
	v_pk_fma_f32 v[108:109], v[108:109], v[158:159], v[162:163]
	global_store_dwordx4 v[166:167], v[108:111], off
	global_load_dwordx4 v[158:161], v[144:145], off offset:16
	global_load_dwordx4 v[162:165], v[176:177], off offset:16
	s_waitcnt vmcnt(0)
	v_pk_fma_f32 v[106:107], v[106:107], v[160:161], v[164:165]
	v_pk_fma_f32 v[104:105], v[104:105], v[158:159], v[162:163]
	global_store_dwordx4 v[166:167], v[104:107], off offset:16
	global_load_dwordx4 v[158:161], v[126:127], off
	global_load_dwordx4 v[162:165], v[126:127], off offset:16
	s_nop 0
	global_load_dwordx4 v[166:169], v[120:121], off
	global_load_dwordx4 v[170:173], v[120:121], off offset:16
	s_waitcnt vmcnt(3)
	v_pk_add_f32 v[160:161], v[160:161], 1.0 op_sel_hi:[1,0]
	v_pk_add_f32 v[158:159], v[158:159], 1.0 op_sel_hi:[1,0]
	s_waitcnt vmcnt(2)
	v_pk_add_f32 v[164:165], v[164:165], 1.0 op_sel_hi:[1,0]
	v_pk_add_f32 v[162:163], v[162:163], 1.0 op_sel_hi:[1,0]
	s_waitcnt vmcnt(1)
	v_pk_mul_f32 v[160:161], v[168:169], v[160:161]
	v_pk_mul_f32 v[158:159], v[166:167], v[158:159]
	s_waitcnt vmcnt(0)
	v_pk_mul_f32 v[164:165], v[172:173], v[164:165]
	v_pk_mul_f32 v[162:163], v[170:171], v[162:163]
	v_pk_mul_f32 v[160:161], v[110:111], v[160:161]
	v_pk_mul_f32 v[158:159], v[108:109], v[158:159]
	v_pk_mul_f32 v[164:165], v[106:107], v[164:165]
	v_pk_mul_f32 v[162:163], v[104:105], v[162:163]
	v_cvt_pk_bf16_f32 v158, v158, v159
	v_cvt_pk_bf16_f32 v159, v160, v161
	v_cvt_pk_bf16_f32 v160, v162, v163
	v_cvt_pk_bf16_f32 v161, v164, v165
	global_store_dwordx4 v[174:175], v[158:161], off
	global_load_dwordx4 v[158:161], v[122:123], off
	s_nop 0
	global_load_dwordx4 v[162:165], v[176:177], off offset:512
	v_lshl_add_u64 v[166:167], v[118:119], 2, s[14:15]
	s_waitcnt vmcnt(0)
	v_pk_fma_f32 v[102:103], v[102:103], v[160:161], v[164:165]
	v_pk_fma_f32 v[100:101], v[100:101], v[158:159], v[162:163]
	global_store_dwordx4 v[166:167], v[100:103], off
	global_load_dwordx4 v[158:161], v[122:123], off offset:16
	global_load_dwordx4 v[162:165], v[176:177], off offset:528
	s_waitcnt vmcnt(0)
	v_pk_fma_f32 v[160:161], v[98:99], v[160:161], v[164:165]
	v_pk_fma_f32 v[158:159], v[96:97], v[158:159], v[162:163]
	global_store_dwordx4 v[166:167], v[158:161], off offset:16
	global_load_dwordx4 v[162:165], v[116:117], off
	s_nop 0
	global_load_dwordx4 v[166:169], v[116:117], off offset:16
	global_load_dwordx4 v[170:173], v[120:121], off offset:512
	global_load_dwordx4 v[174:177], v[120:121], off offset:528
	v_mul_f32_e32 v96, v109, v109
	v_mul_f32_e32 v97, v111, v111
	v_fmac_f32_e32 v96, v108, v108
	v_fmac_f32_e32 v97, v110, v110
	v_add_f32_e32 v96, v96, v97
	v_mul_f32_e32 v97, v105, v105
	v_mul_f32_e32 v98, v107, v107
	v_fmac_f32_e32 v97, v104, v104
	v_fmac_f32_e32 v98, v106, v106
	v_add_f32_e32 v97, v97, v98
	v_add_f32_e32 v96, v96, v97
	v_mul_f32_e32 v97, v101, v101
	v_mul_f32_e32 v98, v103, v103
	v_fmac_f32_e32 v97, v100, v100
	v_fmac_f32_e32 v98, v102, v102
	v_add_f32_e32 v97, v97, v98
	v_add_f32_e32 v96, v96, v97
	v_mul_f32_e32 v97, v159, v159
	v_mul_f32_e32 v98, v161, v161
	v_fmac_f32_e32 v97, v158, v158
	v_fmac_f32_e32 v98, v160, v160
	v_add_f32_e32 v97, v97, v98
	v_add_f32_e32 v96, v96, v97
	ds_bpermute_b32 v97, v114, v96
	s_waitcnt lgkmcnt(0)
	v_add_f32_e32 v96, v96, v97
	ds_bpermute_b32 v97, v115, v96
	s_waitcnt vmcnt(3)
	v_pk_add_f32 v[98:99], v[164:165], 1.0 op_sel_hi:[1,0]
	v_pk_add_f32 v[104:105], v[162:163], 1.0 op_sel_hi:[1,0]
	s_waitcnt vmcnt(2)
	v_pk_add_f32 v[106:107], v[168:169], 1.0 op_sel_hi:[1,0]
	v_pk_add_f32 v[108:109], v[166:167], 1.0 op_sel_hi:[1,0]
	s_waitcnt vmcnt(1)
	v_pk_mul_f32 v[98:99], v[172:173], v[98:99]
	v_pk_mul_f32 v[104:105], v[170:171], v[104:105]
	s_waitcnt vmcnt(0)
	v_pk_mul_f32 v[106:107], v[176:177], v[106:107]
	v_pk_mul_f32 v[108:109], v[174:175], v[108:109]
	v_pk_mul_f32 v[102:103], v[102:103], v[98:99]
	v_pk_mul_f32 v[98:99], v[100:101], v[104:105]
	v_pk_mul_f32 v[104:105], v[160:161], v[106:107]
	v_pk_mul_f32 v[100:101], v[158:159], v[108:109]
	v_cvt_pk_bf16_f32 v98, v98, v99
	v_cvt_pk_bf16_f32 v99, v102, v103
	v_cvt_pk_bf16_f32 v100, v100, v101
	v_cvt_pk_bf16_f32 v101, v104, v105
	v_lshl_add_u64 v[102:103], v[118:119], 1, s[20:21]
	global_store_dwordx4 v[102:103], v[98:101], off
	s_and_saveexec_b64 s[28:29], s[0:1]
	s_cbranch_execz .LBB0_768
	v_lshl_add_u64 v[98:99], v[112:113], 2, s[18:19]
	s_waitcnt lgkmcnt(0)
	v_add_f32_e32 v96, v96, v97
	global_atomic_add_f32 v[98:99], v96, off
.LBB0_768:
	s_or_b64 exec, exec, s[28:29]
	v_or_b32_e32 v96, 32, v146
	s_waitcnt lgkmcnt(0)
	v_ashrrev_i32_e32 v97, 31, v96
	v_lshlrev_b64 v[118:119], 11, v[96:97]
	v_lshl_add_u64 v[158:159], v[118:119], 0, v[148:149]
	v_readlane_b32 s68, v253, 24
	v_lshlrev_b64 v[106:107], 2, v[158:159]
	v_readlane_b32 s69, v253, 25
	global_load_dwordx4 v[98:101], v[144:145], off
	v_lshl_add_u64 v[158:159], v[158:159], 1, s[20:21]
	v_lshl_add_u64 v[160:161], s[68:69], 0, v[106:107]
	global_load_dwordx4 v[102:105], v[160:161], off
	v_lshl_add_u64 v[106:107], s[14:15], 0, v[106:107]
	v_lshl_add_u64 v[118:119], v[118:119], 0, v[124:125]
	v_readlane_b32 s70, v253, 26
	v_readlane_b32 s71, v253, 27
	v_readlane_b32 s72, v253, 28
	v_readlane_b32 s73, v253, 29
	v_readlane_b32 s74, v253, 30
	v_readlane_b32 s75, v253, 31
	v_readlane_b32 s76, v253, 32
	v_readlane_b32 s77, v253, 33
	v_readlane_b32 s78, v253, 34
	v_readlane_b32 s79, v253, 35
	v_readlane_b32 s80, v253, 36
	v_readlane_b32 s81, v253, 37
	v_readlane_b32 s82, v253, 38
	v_readlane_b32 s83, v253, 39
	s_waitcnt vmcnt(0)
	v_pk_fma_f32 v[94:95], v[94:95], v[100:101], v[104:105]
	v_pk_fma_f32 v[92:93], v[92:93], v[98:99], v[102:103]
	global_store_dwordx4 v[106:107], v[92:95], off
	global_load_dwordx4 v[98:101], v[144:145], off offset:16
	global_load_dwordx4 v[102:105], v[160:161], off offset:16
	s_waitcnt vmcnt(0)
	v_pk_fma_f32 v[90:91], v[90:91], v[100:101], v[104:105]
	v_pk_fma_f32 v[88:89], v[88:89], v[98:99], v[102:103]
	global_store_dwordx4 v[106:107], v[88:91], off offset:16
	global_load_dwordx4 v[98:101], v[126:127], off
	global_load_dwordx4 v[102:105], v[126:127], off offset:16
	s_nop 0
	global_load_dwordx4 v[106:109], v[120:121], off
	global_load_dwordx4 v[110:113], v[120:121], off offset:16
	s_waitcnt vmcnt(3)
	v_pk_add_f32 v[100:101], v[100:101], 1.0 op_sel_hi:[1,0]
	v_pk_add_f32 v[98:99], v[98:99], 1.0 op_sel_hi:[1,0]
	s_waitcnt vmcnt(2)
	v_pk_add_f32 v[104:105], v[104:105], 1.0 op_sel_hi:[1,0]
	v_pk_add_f32 v[102:103], v[102:103], 1.0 op_sel_hi:[1,0]
	s_waitcnt vmcnt(1)
	v_pk_mul_f32 v[100:101], v[108:109], v[100:101]
	v_pk_mul_f32 v[98:99], v[106:107], v[98:99]
	s_waitcnt vmcnt(0)
	v_pk_mul_f32 v[104:105], v[112:113], v[104:105]
	v_pk_mul_f32 v[102:103], v[110:111], v[102:103]
	v_pk_mul_f32 v[100:101], v[94:95], v[100:101]
	v_pk_mul_f32 v[98:99], v[92:93], v[98:99]
	v_pk_mul_f32 v[104:105], v[90:91], v[104:105]
	v_pk_mul_f32 v[102:103], v[88:89], v[102:103]
	v_cvt_pk_bf16_f32 v98, v98, v99
	v_cvt_pk_bf16_f32 v99, v100, v101
	v_cvt_pk_bf16_f32 v100, v102, v103
	v_cvt_pk_bf16_f32 v101, v104, v105
	global_store_dwordx4 v[158:159], v[98:101], off
	global_load_dwordx4 v[98:101], v[122:123], off
	s_nop 0
	global_load_dwordx4 v[102:105], v[160:161], off offset:512
	v_lshl_add_u64 v[106:107], v[118:119], 2, s[14:15]
	s_waitcnt vmcnt(0)
	v_pk_fma_f32 v[86:87], v[86:87], v[100:101], v[104:105]
	v_pk_fma_f32 v[84:85], v[84:85], v[98:99], v[102:103]
	global_store_dwordx4 v[106:107], v[84:87], off
	global_load_dwordx4 v[98:101], v[122:123], off offset:16
	global_load_dwordx4 v[102:105], v[160:161], off offset:528
	s_waitcnt vmcnt(0)
	v_pk_fma_f32 v[100:101], v[82:83], v[100:101], v[104:105]
	v_pk_fma_f32 v[98:99], v[80:81], v[98:99], v[102:103]
	global_store_dwordx4 v[106:107], v[98:101], off offset:16
	global_load_dwordx4 v[102:105], v[116:117], off
	s_nop 0
	global_load_dwordx4 v[106:109], v[116:117], off offset:16
	global_load_dwordx4 v[110:113], v[120:121], off offset:512
	global_load_dwordx4 v[158:161], v[120:121], off offset:528
	v_mul_f32_e32 v80, v93, v93
	v_mul_f32_e32 v81, v95, v95
	v_fmac_f32_e32 v80, v92, v92
	v_fmac_f32_e32 v81, v94, v94
	v_add_f32_e32 v80, v80, v81
	v_mul_f32_e32 v81, v89, v89
	v_mul_f32_e32 v82, v91, v91
	v_fmac_f32_e32 v81, v88, v88
	v_fmac_f32_e32 v82, v90, v90
	v_add_f32_e32 v81, v81, v82
	v_add_f32_e32 v80, v80, v81
	v_mul_f32_e32 v81, v85, v85
	v_mul_f32_e32 v82, v87, v87
	v_fmac_f32_e32 v81, v84, v84
	v_fmac_f32_e32 v82, v86, v86
	v_add_f32_e32 v81, v81, v82
	v_add_f32_e32 v80, v80, v81
	v_mul_f32_e32 v81, v99, v99
	v_mul_f32_e32 v82, v101, v101
	v_fmac_f32_e32 v81, v98, v98
	v_fmac_f32_e32 v82, v100, v100
	v_add_f32_e32 v81, v81, v82
	v_add_f32_e32 v80, v80, v81
	ds_bpermute_b32 v81, v114, v80
	s_waitcnt lgkmcnt(0)
	v_add_f32_e32 v80, v80, v81
	ds_bpermute_b32 v81, v115, v80
	s_waitcnt vmcnt(3)
	v_pk_add_f32 v[82:83], v[104:105], 1.0 op_sel_hi:[1,0]
	v_pk_add_f32 v[88:89], v[102:103], 1.0 op_sel_hi:[1,0]
	s_waitcnt vmcnt(2)
	v_pk_add_f32 v[90:91], v[108:109], 1.0 op_sel_hi:[1,0]
	v_pk_add_f32 v[92:93], v[106:107], 1.0 op_sel_hi:[1,0]
	s_waitcnt vmcnt(1)
	v_pk_mul_f32 v[82:83], v[112:113], v[82:83]
	v_pk_mul_f32 v[88:89], v[110:111], v[88:89]
	s_waitcnt vmcnt(0)
	v_pk_mul_f32 v[90:91], v[160:161], v[90:91]
	v_pk_mul_f32 v[92:93], v[158:159], v[92:93]
	v_pk_mul_f32 v[86:87], v[86:87], v[82:83]
	v_pk_mul_f32 v[82:83], v[84:85], v[88:89]
	v_pk_mul_f32 v[88:89], v[100:101], v[90:91]
	v_pk_mul_f32 v[84:85], v[98:99], v[92:93]
	v_cvt_pk_bf16_f32 v82, v82, v83
	v_cvt_pk_bf16_f32 v83, v86, v87
	v_cvt_pk_bf16_f32 v84, v84, v85
	v_cvt_pk_bf16_f32 v85, v88, v89
	v_lshl_add_u64 v[86:87], v[118:119], 1, s[20:21]
	global_store_dwordx4 v[86:87], v[82:85], off
	s_and_saveexec_b64 s[28:29], s[0:1]
	s_cbranch_execz .LBB0_770
	v_lshl_add_u64 v[82:83], v[96:97], 2, s[18:19]
	s_waitcnt lgkmcnt(0)
	v_add_f32_e32 v80, v80, v81
	global_atomic_add_f32 v[82:83], v80, off
.LBB0_770:
	s_or_b64 exec, exec, s[28:29]
	v_or_b32_e32 v80, 48, v146
	s_waitcnt lgkmcnt(0)
	v_ashrrev_i32_e32 v81, 31, v80
	v_lshlrev_b64 v[98:99], 11, v[80:81]
	v_lshl_add_u64 v[100:101], v[98:99], 0, v[148:149]
	v_readlane_b32 s68, v253, 24
	v_lshlrev_b64 v[90:91], 2, v[100:101]
	v_readlane_b32 s69, v253, 25
	global_load_dwordx4 v[82:85], v[144:145], off
	v_lshl_add_u64 v[100:101], v[100:101], 1, s[20:21]
	v_lshl_add_u64 v[102:103], s[68:69], 0, v[90:91]
	global_load_dwordx4 v[86:89], v[102:103], off
	v_lshl_add_u64 v[90:91], s[14:15], 0, v[90:91]
	v_lshl_add_u64 v[104:105], v[98:99], 0, v[124:125]
	v_readlane_b32 s70, v253, 26
	v_readlane_b32 s71, v253, 27
	v_readlane_b32 s72, v253, 28
	v_readlane_b32 s73, v253, 29
	v_readlane_b32 s74, v253, 30
	v_readlane_b32 s75, v253, 31
	v_readlane_b32 s76, v253, 32
	v_readlane_b32 s77, v253, 33
	v_readlane_b32 s78, v253, 34
	v_readlane_b32 s79, v253, 35
	v_readlane_b32 s80, v253, 36
	v_readlane_b32 s81, v253, 37
	v_readlane_b32 s82, v253, 38
	v_readlane_b32 s83, v253, 39
	s_waitcnt vmcnt(0)
	v_pk_fma_f32 v[78:79], v[78:79], v[84:85], v[88:89]
	v_pk_fma_f32 v[76:77], v[76:77], v[82:83], v[86:87]
	global_store_dwordx4 v[90:91], v[76:79], off
	global_load_dwordx4 v[82:85], v[144:145], off offset:16
	global_load_dwordx4 v[86:89], v[102:103], off offset:16
	s_waitcnt vmcnt(0)
	v_pk_fma_f32 v[74:75], v[74:75], v[84:85], v[88:89]
	v_pk_fma_f32 v[72:73], v[72:73], v[82:83], v[86:87]
	global_store_dwordx4 v[90:91], v[72:75], off offset:16
	global_load_dwordx4 v[82:85], v[126:127], off
	global_load_dwordx4 v[86:89], v[126:127], off offset:16
	s_nop 0
	global_load_dwordx4 v[90:93], v[120:121], off
	global_load_dwordx4 v[94:97], v[120:121], off offset:16
	s_waitcnt vmcnt(3)
	v_pk_add_f32 v[84:85], v[84:85], 1.0 op_sel_hi:[1,0]
	v_pk_add_f32 v[82:83], v[82:83], 1.0 op_sel_hi:[1,0]
	s_waitcnt vmcnt(2)
	v_pk_add_f32 v[88:89], v[88:89], 1.0 op_sel_hi:[1,0]
	v_pk_add_f32 v[86:87], v[86:87], 1.0 op_sel_hi:[1,0]
	s_waitcnt vmcnt(1)
	v_pk_mul_f32 v[84:85], v[92:93], v[84:85]
	v_pk_mul_f32 v[82:83], v[90:91], v[82:83]
	s_waitcnt vmcnt(0)
	v_pk_mul_f32 v[88:89], v[96:97], v[88:89]
	v_pk_mul_f32 v[86:87], v[94:95], v[86:87]
	v_pk_mul_f32 v[84:85], v[78:79], v[84:85]
	v_pk_mul_f32 v[82:83], v[76:77], v[82:83]
	v_pk_mul_f32 v[88:89], v[74:75], v[88:89]
	v_pk_mul_f32 v[86:87], v[72:73], v[86:87]
	v_cvt_pk_bf16_f32 v82, v82, v83
	v_cvt_pk_bf16_f32 v83, v84, v85
	v_cvt_pk_bf16_f32 v84, v86, v87
	v_cvt_pk_bf16_f32 v85, v88, v89
	global_store_dwordx4 v[100:101], v[82:85], off
	global_load_dwordx4 v[82:85], v[122:123], off
	s_nop 0
	global_load_dwordx4 v[86:89], v[102:103], off offset:512
	v_lshl_add_u64 v[90:91], v[104:105], 2, s[14:15]
	s_waitcnt vmcnt(0)
	v_pk_fma_f32 v[70:71], v[70:71], v[84:85], v[88:89]
	v_pk_fma_f32 v[68:69], v[68:69], v[82:83], v[86:87]
	global_store_dwordx4 v[90:91], v[68:71], off
	global_load_dwordx4 v[82:85], v[122:123], off offset:16
	global_load_dwordx4 v[86:89], v[102:103], off offset:528
	s_waitcnt vmcnt(0)
	v_pk_fma_f32 v[84:85], v[66:67], v[84:85], v[88:89]
	v_pk_fma_f32 v[82:83], v[64:65], v[82:83], v[86:87]
	global_store_dwordx4 v[90:91], v[82:85], off offset:16
	global_load_dwordx4 v[86:89], v[116:117], off
	s_nop 0
	global_load_dwordx4 v[90:93], v[116:117], off offset:16
	global_load_dwordx4 v[94:97], v[120:121], off offset:512
	global_load_dwordx4 v[98:101], v[120:121], off offset:528
	v_mul_f32_e32 v64, v77, v77
	v_mul_f32_e32 v65, v79, v79
	v_fmac_f32_e32 v64, v76, v76
	v_fmac_f32_e32 v65, v78, v78
	v_add_f32_e32 v64, v64, v65
	v_mul_f32_e32 v65, v73, v73
	v_mul_f32_e32 v66, v75, v75
	v_fmac_f32_e32 v65, v72, v72
	v_fmac_f32_e32 v66, v74, v74
	v_add_f32_e32 v65, v65, v66
	v_add_f32_e32 v64, v64, v65
	v_mul_f32_e32 v65, v69, v69
	v_mul_f32_e32 v66, v71, v71
	v_fmac_f32_e32 v65, v68, v68
	v_fmac_f32_e32 v66, v70, v70
	v_add_f32_e32 v65, v65, v66
	v_add_f32_e32 v64, v64, v65
	v_mul_f32_e32 v65, v83, v83
	v_mul_f32_e32 v66, v85, v85
	v_fmac_f32_e32 v65, v82, v82
	v_fmac_f32_e32 v66, v84, v84
	v_add_f32_e32 v65, v65, v66
	v_add_f32_e32 v64, v64, v65
	ds_bpermute_b32 v65, v114, v64
	s_waitcnt lgkmcnt(0)
	v_add_f32_e32 v64, v64, v65
	ds_bpermute_b32 v65, v115, v64
	s_waitcnt vmcnt(3)
	v_pk_add_f32 v[66:67], v[88:89], 1.0 op_sel_hi:[1,0]
	v_pk_add_f32 v[72:73], v[86:87], 1.0 op_sel_hi:[1,0]
	s_waitcnt vmcnt(2)
	v_pk_add_f32 v[74:75], v[92:93], 1.0 op_sel_hi:[1,0]
	v_pk_add_f32 v[76:77], v[90:91], 1.0 op_sel_hi:[1,0]
	s_waitcnt vmcnt(1)
	v_pk_mul_f32 v[66:67], v[96:97], v[66:67]
	v_pk_mul_f32 v[72:73], v[94:95], v[72:73]
	s_waitcnt vmcnt(0)
	v_pk_mul_f32 v[74:75], v[100:101], v[74:75]
	v_pk_mul_f32 v[76:77], v[98:99], v[76:77]
	v_pk_mul_f32 v[70:71], v[70:71], v[66:67]
	v_pk_mul_f32 v[66:67], v[68:69], v[72:73]
	v_pk_mul_f32 v[72:73], v[84:85], v[74:75]
	v_pk_mul_f32 v[68:69], v[82:83], v[76:77]
	v_cvt_pk_bf16_f32 v66, v66, v67
	v_cvt_pk_bf16_f32 v67, v70, v71
	v_cvt_pk_bf16_f32 v68, v68, v69
	v_cvt_pk_bf16_f32 v69, v72, v73
	v_lshl_add_u64 v[70:71], v[104:105], 1, s[20:21]
	global_store_dwordx4 v[70:71], v[66:69], off
	s_and_saveexec_b64 s[28:29], s[0:1]
	s_cbranch_execz .LBB0_772
	v_lshl_add_u64 v[66:67], v[80:81], 2, s[18:19]
	s_waitcnt lgkmcnt(0)
	v_add_f32_e32 v64, v64, v65
	global_atomic_add_f32 v[66:67], v64, off
.LBB0_772:
	s_or_b64 exec, exec, s[28:29]
	v_add_u32_e32 v64, 0x80, v146
	s_waitcnt lgkmcnt(0)
	v_ashrrev_i32_e32 v65, 31, v64
	v_lshlrev_b64 v[82:83], 11, v[64:65]
	v_lshl_add_u64 v[84:85], v[82:83], 0, v[148:149]
	v_readlane_b32 s68, v253, 24
	v_lshlrev_b64 v[74:75], 2, v[84:85]
	v_readlane_b32 s69, v253, 25
	global_load_dwordx4 v[66:69], v[144:145], off
	v_lshl_add_u64 v[84:85], v[84:85], 1, s[20:21]
	v_lshl_add_u64 v[86:87], s[68:69], 0, v[74:75]
	global_load_dwordx4 v[70:73], v[86:87], off
	v_lshl_add_u64 v[74:75], s[14:15], 0, v[74:75]
	v_lshl_add_u64 v[88:89], v[82:83], 0, v[124:125]
	v_readlane_b32 s70, v253, 26
	v_readlane_b32 s71, v253, 27
	v_readlane_b32 s72, v253, 28
	v_readlane_b32 s73, v253, 29
	v_readlane_b32 s74, v253, 30
	v_readlane_b32 s75, v253, 31
	v_readlane_b32 s76, v253, 32
	v_readlane_b32 s77, v253, 33
	v_readlane_b32 s78, v253, 34
	v_readlane_b32 s79, v253, 35
	v_readlane_b32 s80, v253, 36
	v_readlane_b32 s81, v253, 37
	v_readlane_b32 s82, v253, 38
	v_readlane_b32 s83, v253, 39
	s_waitcnt vmcnt(0)
	v_pk_fma_f32 v[62:63], v[62:63], v[68:69], v[72:73]
	v_pk_fma_f32 v[60:61], v[60:61], v[66:67], v[70:71]
	global_store_dwordx4 v[74:75], v[60:63], off
	global_load_dwordx4 v[66:69], v[144:145], off offset:16
	global_load_dwordx4 v[70:73], v[86:87], off offset:16
	s_waitcnt vmcnt(0)
	v_pk_fma_f32 v[58:59], v[58:59], v[68:69], v[72:73]
	v_pk_fma_f32 v[56:57], v[56:57], v[66:67], v[70:71]
	global_store_dwordx4 v[74:75], v[56:59], off offset:16
	global_load_dwordx4 v[66:69], v[126:127], off
	global_load_dwordx4 v[70:73], v[126:127], off offset:16
	s_nop 0
	global_load_dwordx4 v[74:77], v[120:121], off
	global_load_dwordx4 v[78:81], v[120:121], off offset:16
	s_waitcnt vmcnt(3)
	v_pk_add_f32 v[68:69], v[68:69], 1.0 op_sel_hi:[1,0]
	v_pk_add_f32 v[66:67], v[66:67], 1.0 op_sel_hi:[1,0]
	s_waitcnt vmcnt(2)
	v_pk_add_f32 v[72:73], v[72:73], 1.0 op_sel_hi:[1,0]
	v_pk_add_f32 v[70:71], v[70:71], 1.0 op_sel_hi:[1,0]
	s_waitcnt vmcnt(1)
	v_pk_mul_f32 v[68:69], v[76:77], v[68:69]
	v_pk_mul_f32 v[66:67], v[74:75], v[66:67]
	s_waitcnt vmcnt(0)
	v_pk_mul_f32 v[72:73], v[80:81], v[72:73]
	v_pk_mul_f32 v[70:71], v[78:79], v[70:71]
	v_pk_mul_f32 v[68:69], v[62:63], v[68:69]
	v_pk_mul_f32 v[66:67], v[60:61], v[66:67]
	v_pk_mul_f32 v[72:73], v[58:59], v[72:73]
	v_pk_mul_f32 v[70:71], v[56:57], v[70:71]
	v_cvt_pk_bf16_f32 v66, v66, v67
	v_cvt_pk_bf16_f32 v67, v68, v69
	v_cvt_pk_bf16_f32 v68, v70, v71
	v_cvt_pk_bf16_f32 v69, v72, v73
	global_store_dwordx4 v[84:85], v[66:69], off
	global_load_dwordx4 v[66:69], v[122:123], off
	s_nop 0
	global_load_dwordx4 v[70:73], v[86:87], off offset:512
	v_lshl_add_u64 v[74:75], v[88:89], 2, s[14:15]
	s_waitcnt vmcnt(0)
	v_pk_fma_f32 v[54:55], v[54:55], v[68:69], v[72:73]
	v_pk_fma_f32 v[52:53], v[52:53], v[66:67], v[70:71]
	global_store_dwordx4 v[74:75], v[52:55], off
	global_load_dwordx4 v[66:69], v[122:123], off offset:16
	global_load_dwordx4 v[70:73], v[86:87], off offset:528
	s_waitcnt vmcnt(0)
	v_pk_fma_f32 v[68:69], v[50:51], v[68:69], v[72:73]
	v_pk_fma_f32 v[66:67], v[48:49], v[66:67], v[70:71]
	global_store_dwordx4 v[74:75], v[66:69], off offset:16
	global_load_dwordx4 v[70:73], v[116:117], off
	s_nop 0
	global_load_dwordx4 v[74:77], v[116:117], off offset:16
	global_load_dwordx4 v[78:81], v[120:121], off offset:512
	global_load_dwordx4 v[82:85], v[120:121], off offset:528
	v_mul_f32_e32 v48, v61, v61
	v_mul_f32_e32 v49, v63, v63
	v_fmac_f32_e32 v48, v60, v60
	v_fmac_f32_e32 v49, v62, v62
	v_add_f32_e32 v48, v48, v49
	v_mul_f32_e32 v49, v57, v57
	v_mul_f32_e32 v50, v59, v59
	v_fmac_f32_e32 v49, v56, v56
	v_fmac_f32_e32 v50, v58, v58
	v_add_f32_e32 v49, v49, v50
	v_add_f32_e32 v48, v48, v49
	v_mul_f32_e32 v49, v53, v53
	v_mul_f32_e32 v50, v55, v55
	v_fmac_f32_e32 v49, v52, v52
	v_fmac_f32_e32 v50, v54, v54
	v_add_f32_e32 v49, v49, v50
	v_add_f32_e32 v48, v48, v49
	v_mul_f32_e32 v49, v67, v67
	v_mul_f32_e32 v50, v69, v69
	v_fmac_f32_e32 v49, v66, v66
	v_fmac_f32_e32 v50, v68, v68
	v_add_f32_e32 v49, v49, v50
	v_add_f32_e32 v48, v48, v49
	ds_bpermute_b32 v49, v114, v48
	s_waitcnt lgkmcnt(0)
	v_add_f32_e32 v48, v48, v49
	ds_bpermute_b32 v49, v115, v48
	s_waitcnt vmcnt(3)
	v_pk_add_f32 v[50:51], v[72:73], 1.0 op_sel_hi:[1,0]
	v_pk_add_f32 v[56:57], v[70:71], 1.0 op_sel_hi:[1,0]
	s_waitcnt vmcnt(2)
	v_pk_add_f32 v[58:59], v[76:77], 1.0 op_sel_hi:[1,0]
	v_pk_add_f32 v[60:61], v[74:75], 1.0 op_sel_hi:[1,0]
	s_waitcnt vmcnt(1)
	v_pk_mul_f32 v[50:51], v[80:81], v[50:51]
	v_pk_mul_f32 v[56:57], v[78:79], v[56:57]
	s_waitcnt vmcnt(0)
	v_pk_mul_f32 v[58:59], v[84:85], v[58:59]
	v_pk_mul_f32 v[60:61], v[82:83], v[60:61]
	v_pk_mul_f32 v[54:55], v[54:55], v[50:51]
	v_pk_mul_f32 v[50:51], v[52:53], v[56:57]
	v_pk_mul_f32 v[56:57], v[68:69], v[58:59]
	v_pk_mul_f32 v[52:53], v[66:67], v[60:61]
	v_cvt_pk_bf16_f32 v50, v50, v51
	v_cvt_pk_bf16_f32 v51, v54, v55
	v_cvt_pk_bf16_f32 v52, v52, v53
	v_cvt_pk_bf16_f32 v53, v56, v57
	v_lshl_add_u64 v[54:55], v[88:89], 1, s[20:21]
	global_store_dwordx4 v[54:55], v[50:53], off
	s_and_saveexec_b64 s[28:29], s[0:1]
	s_cbranch_execz .LBB0_774
	v_lshl_add_u64 v[50:51], v[64:65], 2, s[18:19]
	s_waitcnt lgkmcnt(0)
	v_add_f32_e32 v48, v48, v49
	global_atomic_add_f32 v[50:51], v48, off
.LBB0_774:
	s_or_b64 exec, exec, s[28:29]
	v_add_u32_e32 v48, 0x90, v146
	s_waitcnt lgkmcnt(0)
	v_ashrrev_i32_e32 v49, 31, v48
	v_lshlrev_b64 v[66:67], 11, v[48:49]
	v_lshl_add_u64 v[68:69], v[66:67], 0, v[148:149]
	v_readlane_b32 s68, v253, 24
	v_lshlrev_b64 v[58:59], 2, v[68:69]
	v_readlane_b32 s69, v253, 25
	global_load_dwordx4 v[50:53], v[144:145], off
	v_lshl_add_u64 v[68:69], v[68:69], 1, s[20:21]
	v_lshl_add_u64 v[70:71], s[68:69], 0, v[58:59]
	global_load_dwordx4 v[54:57], v[70:71], off
	v_lshl_add_u64 v[58:59], s[14:15], 0, v[58:59]
	v_lshl_add_u64 v[72:73], v[66:67], 0, v[124:125]
	v_readlane_b32 s70, v253, 26
	v_readlane_b32 s71, v253, 27
	v_readlane_b32 s72, v253, 28
	v_readlane_b32 s73, v253, 29
	v_readlane_b32 s74, v253, 30
	v_readlane_b32 s75, v253, 31
	v_readlane_b32 s76, v253, 32
	v_readlane_b32 s77, v253, 33
	v_readlane_b32 s78, v253, 34
	v_readlane_b32 s79, v253, 35
	v_readlane_b32 s80, v253, 36
	v_readlane_b32 s81, v253, 37
	v_readlane_b32 s82, v253, 38
	v_readlane_b32 s83, v253, 39
	s_waitcnt vmcnt(0)
	v_pk_fma_f32 v[46:47], v[46:47], v[52:53], v[56:57]
	v_pk_fma_f32 v[44:45], v[44:45], v[50:51], v[54:55]
	global_store_dwordx4 v[58:59], v[44:47], off
	global_load_dwordx4 v[50:53], v[144:145], off offset:16
	global_load_dwordx4 v[54:57], v[70:71], off offset:16
	s_waitcnt vmcnt(0)
	v_pk_fma_f32 v[42:43], v[42:43], v[52:53], v[56:57]
	v_pk_fma_f32 v[40:41], v[40:41], v[50:51], v[54:55]
	global_store_dwordx4 v[58:59], v[40:43], off offset:16
	global_load_dwordx4 v[50:53], v[126:127], off
	global_load_dwordx4 v[54:57], v[126:127], off offset:16
	s_nop 0
	global_load_dwordx4 v[58:61], v[120:121], off
	global_load_dwordx4 v[62:65], v[120:121], off offset:16
	s_waitcnt vmcnt(3)
	v_pk_add_f32 v[52:53], v[52:53], 1.0 op_sel_hi:[1,0]
	v_pk_add_f32 v[50:51], v[50:51], 1.0 op_sel_hi:[1,0]
	s_waitcnt vmcnt(2)
	v_pk_add_f32 v[56:57], v[56:57], 1.0 op_sel_hi:[1,0]
	v_pk_add_f32 v[54:55], v[54:55], 1.0 op_sel_hi:[1,0]
	s_waitcnt vmcnt(1)
	v_pk_mul_f32 v[52:53], v[60:61], v[52:53]
	v_pk_mul_f32 v[50:51], v[58:59], v[50:51]
	s_waitcnt vmcnt(0)
	v_pk_mul_f32 v[56:57], v[64:65], v[56:57]
	v_pk_mul_f32 v[54:55], v[62:63], v[54:55]
	v_pk_mul_f32 v[52:53], v[46:47], v[52:53]
	v_pk_mul_f32 v[50:51], v[44:45], v[50:51]
	v_pk_mul_f32 v[56:57], v[42:43], v[56:57]
	v_pk_mul_f32 v[54:55], v[40:41], v[54:55]
	v_cvt_pk_bf16_f32 v50, v50, v51
	v_cvt_pk_bf16_f32 v51, v52, v53
	v_cvt_pk_bf16_f32 v52, v54, v55
	v_cvt_pk_bf16_f32 v53, v56, v57
	global_store_dwordx4 v[68:69], v[50:53], off
	global_load_dwordx4 v[50:53], v[122:123], off
	s_nop 0
	global_load_dwordx4 v[54:57], v[70:71], off offset:512
	v_lshl_add_u64 v[58:59], v[72:73], 2, s[14:15]
	s_waitcnt vmcnt(0)
	v_pk_fma_f32 v[38:39], v[38:39], v[52:53], v[56:57]
	v_pk_fma_f32 v[36:37], v[36:37], v[50:51], v[54:55]
	global_store_dwordx4 v[58:59], v[36:39], off
	global_load_dwordx4 v[50:53], v[122:123], off offset:16
	global_load_dwordx4 v[54:57], v[70:71], off offset:528
	s_waitcnt vmcnt(0)
	v_pk_fma_f32 v[52:53], v[34:35], v[52:53], v[56:57]
	v_pk_fma_f32 v[50:51], v[32:33], v[50:51], v[54:55]
	global_store_dwordx4 v[58:59], v[50:53], off offset:16
	global_load_dwordx4 v[54:57], v[116:117], off
	s_nop 0
	global_load_dwordx4 v[58:61], v[116:117], off offset:16
	global_load_dwordx4 v[62:65], v[120:121], off offset:512
	global_load_dwordx4 v[66:69], v[120:121], off offset:528
	v_mul_f32_e32 v32, v45, v45
	v_mul_f32_e32 v33, v47, v47
	v_fmac_f32_e32 v32, v44, v44
	v_fmac_f32_e32 v33, v46, v46
	v_add_f32_e32 v32, v32, v33
	v_mul_f32_e32 v33, v41, v41
	v_mul_f32_e32 v34, v43, v43
	v_fmac_f32_e32 v33, v40, v40
	v_fmac_f32_e32 v34, v42, v42
	v_add_f32_e32 v33, v33, v34
	v_add_f32_e32 v32, v32, v33
	v_mul_f32_e32 v33, v37, v37
	v_mul_f32_e32 v34, v39, v39
	v_fmac_f32_e32 v33, v36, v36
	v_fmac_f32_e32 v34, v38, v38
	v_add_f32_e32 v33, v33, v34
	v_add_f32_e32 v32, v32, v33
	v_mul_f32_e32 v33, v51, v51
	v_mul_f32_e32 v34, v53, v53
	v_fmac_f32_e32 v33, v50, v50
	v_fmac_f32_e32 v34, v52, v52
	v_add_f32_e32 v33, v33, v34
	v_add_f32_e32 v32, v32, v33
	ds_bpermute_b32 v33, v114, v32
	s_waitcnt lgkmcnt(0)
	v_add_f32_e32 v32, v32, v33
	ds_bpermute_b32 v33, v115, v32
	s_waitcnt vmcnt(3)
	v_pk_add_f32 v[34:35], v[56:57], 1.0 op_sel_hi:[1,0]
	v_pk_add_f32 v[40:41], v[54:55], 1.0 op_sel_hi:[1,0]
	s_waitcnt vmcnt(2)
	v_pk_add_f32 v[42:43], v[60:61], 1.0 op_sel_hi:[1,0]
	v_pk_add_f32 v[44:45], v[58:59], 1.0 op_sel_hi:[1,0]
	s_waitcnt vmcnt(1)
	v_pk_mul_f32 v[34:35], v[64:65], v[34:35]
	v_pk_mul_f32 v[40:41], v[62:63], v[40:41]
	s_waitcnt vmcnt(0)
	v_pk_mul_f32 v[42:43], v[68:69], v[42:43]
	v_pk_mul_f32 v[44:45], v[66:67], v[44:45]
	v_pk_mul_f32 v[38:39], v[38:39], v[34:35]
	v_pk_mul_f32 v[34:35], v[36:37], v[40:41]
	v_pk_mul_f32 v[40:41], v[52:53], v[42:43]
	v_pk_mul_f32 v[36:37], v[50:51], v[44:45]
	v_cvt_pk_bf16_f32 v34, v34, v35
	v_cvt_pk_bf16_f32 v35, v38, v39
	v_cvt_pk_bf16_f32 v36, v36, v37
	v_cvt_pk_bf16_f32 v37, v40, v41
	v_lshl_add_u64 v[38:39], v[72:73], 1, s[20:21]
	global_store_dwordx4 v[38:39], v[34:37], off
	s_and_saveexec_b64 s[28:29], s[0:1]
	s_cbranch_execz .LBB0_776
	v_lshl_add_u64 v[34:35], v[48:49], 2, s[18:19]
	s_waitcnt lgkmcnt(0)
	v_add_f32_e32 v32, v32, v33
	global_atomic_add_f32 v[34:35], v32, off
.LBB0_776:
	s_or_b64 exec, exec, s[28:29]
	v_add_u32_e32 v32, 0xa0, v146
	s_waitcnt lgkmcnt(0)
	v_ashrrev_i32_e32 v33, 31, v32
	v_lshlrev_b64 v[50:51], 11, v[32:33]
	v_lshl_add_u64 v[52:53], v[50:51], 0, v[148:149]
	v_readlane_b32 s68, v253, 24
	v_lshlrev_b64 v[42:43], 2, v[52:53]
	v_readlane_b32 s69, v253, 25
	global_load_dwordx4 v[34:37], v[144:145], off
	v_lshl_add_u64 v[52:53], v[52:53], 1, s[20:21]
	v_lshl_add_u64 v[54:55], s[68:69], 0, v[42:43]
	global_load_dwordx4 v[38:41], v[54:55], off
	v_lshl_add_u64 v[42:43], s[14:15], 0, v[42:43]
	v_lshl_add_u64 v[56:57], v[50:51], 0, v[124:125]
	v_readlane_b32 s70, v253, 26
	v_readlane_b32 s71, v253, 27
	v_readlane_b32 s72, v253, 28
	v_readlane_b32 s73, v253, 29
	v_readlane_b32 s74, v253, 30
	v_readlane_b32 s75, v253, 31
	v_readlane_b32 s76, v253, 32
	v_readlane_b32 s77, v253, 33
	v_readlane_b32 s78, v253, 34
	v_readlane_b32 s79, v253, 35
	v_readlane_b32 s80, v253, 36
	v_readlane_b32 s81, v253, 37
	v_readlane_b32 s82, v253, 38
	v_readlane_b32 s83, v253, 39
	s_waitcnt vmcnt(0)
	v_pk_fma_f32 v[30:31], v[30:31], v[36:37], v[40:41]
	v_pk_fma_f32 v[28:29], v[28:29], v[34:35], v[38:39]
	global_store_dwordx4 v[42:43], v[28:31], off
	global_load_dwordx4 v[34:37], v[144:145], off offset:16
	global_load_dwordx4 v[38:41], v[54:55], off offset:16
	s_waitcnt vmcnt(0)
	v_pk_fma_f32 v[26:27], v[26:27], v[36:37], v[40:41]
	v_pk_fma_f32 v[24:25], v[24:25], v[34:35], v[38:39]
	global_store_dwordx4 v[42:43], v[24:27], off offset:16
	global_load_dwordx4 v[34:37], v[126:127], off
	global_load_dwordx4 v[38:41], v[126:127], off offset:16
	s_nop 0
	global_load_dwordx4 v[42:45], v[120:121], off
	global_load_dwordx4 v[46:49], v[120:121], off offset:16
	s_waitcnt vmcnt(3)
	v_pk_add_f32 v[36:37], v[36:37], 1.0 op_sel_hi:[1,0]
	v_pk_add_f32 v[34:35], v[34:35], 1.0 op_sel_hi:[1,0]
	s_waitcnt vmcnt(2)
	v_pk_add_f32 v[40:41], v[40:41], 1.0 op_sel_hi:[1,0]
	v_pk_add_f32 v[38:39], v[38:39], 1.0 op_sel_hi:[1,0]
	s_waitcnt vmcnt(1)
	v_pk_mul_f32 v[36:37], v[44:45], v[36:37]
	v_pk_mul_f32 v[34:35], v[42:43], v[34:35]
	s_waitcnt vmcnt(0)
	v_pk_mul_f32 v[40:41], v[48:49], v[40:41]
	v_pk_mul_f32 v[38:39], v[46:47], v[38:39]
	v_pk_mul_f32 v[36:37], v[30:31], v[36:37]
	v_pk_mul_f32 v[34:35], v[28:29], v[34:35]
	v_pk_mul_f32 v[40:41], v[26:27], v[40:41]
	v_pk_mul_f32 v[38:39], v[24:25], v[38:39]
	v_cvt_pk_bf16_f32 v34, v34, v35
	v_cvt_pk_bf16_f32 v35, v36, v37
	v_cvt_pk_bf16_f32 v36, v38, v39
	v_cvt_pk_bf16_f32 v37, v40, v41
	global_store_dwordx4 v[52:53], v[34:37], off
	global_load_dwordx4 v[34:37], v[122:123], off
	s_nop 0
	global_load_dwordx4 v[38:41], v[54:55], off offset:512
	v_lshl_add_u64 v[42:43], v[56:57], 2, s[14:15]
	s_waitcnt vmcnt(0)
	v_pk_fma_f32 v[22:23], v[22:23], v[36:37], v[40:41]
	v_pk_fma_f32 v[20:21], v[20:21], v[34:35], v[38:39]
	global_store_dwordx4 v[42:43], v[20:23], off
	global_load_dwordx4 v[34:37], v[122:123], off offset:16
	global_load_dwordx4 v[38:41], v[54:55], off offset:528
	s_waitcnt vmcnt(0)
	v_pk_fma_f32 v[36:37], v[18:19], v[36:37], v[40:41]
	v_pk_fma_f32 v[34:35], v[16:17], v[34:35], v[38:39]
	global_store_dwordx4 v[42:43], v[34:37], off offset:16
	global_load_dwordx4 v[38:41], v[116:117], off
	s_nop 0
	global_load_dwordx4 v[42:45], v[116:117], off offset:16
	global_load_dwordx4 v[46:49], v[120:121], off offset:512
	global_load_dwordx4 v[50:53], v[120:121], off offset:528
	v_mul_f32_e32 v16, v29, v29
	v_mul_f32_e32 v17, v31, v31
	v_fmac_f32_e32 v16, v28, v28
	v_fmac_f32_e32 v17, v30, v30
	v_add_f32_e32 v16, v16, v17
	v_mul_f32_e32 v17, v25, v25
	v_mul_f32_e32 v18, v27, v27
	v_fmac_f32_e32 v17, v24, v24
	v_fmac_f32_e32 v18, v26, v26
	v_add_f32_e32 v17, v17, v18
	v_add_f32_e32 v16, v16, v17
	v_mul_f32_e32 v17, v21, v21
	v_mul_f32_e32 v18, v23, v23
	v_fmac_f32_e32 v17, v20, v20
	v_fmac_f32_e32 v18, v22, v22
	v_add_f32_e32 v17, v17, v18
	v_add_f32_e32 v16, v16, v17
	v_mul_f32_e32 v17, v35, v35
	v_mul_f32_e32 v18, v37, v37
	v_fmac_f32_e32 v17, v34, v34
	v_fmac_f32_e32 v18, v36, v36
	v_add_f32_e32 v17, v17, v18
	v_add_f32_e32 v16, v16, v17
	ds_bpermute_b32 v17, v114, v16
	s_waitcnt lgkmcnt(0)
	v_add_f32_e32 v16, v16, v17
	ds_bpermute_b32 v17, v115, v16
	s_waitcnt vmcnt(3)
	v_pk_add_f32 v[18:19], v[40:41], 1.0 op_sel_hi:[1,0]
	v_pk_add_f32 v[24:25], v[38:39], 1.0 op_sel_hi:[1,0]
	s_waitcnt vmcnt(2)
	v_pk_add_f32 v[26:27], v[44:45], 1.0 op_sel_hi:[1,0]
	v_pk_add_f32 v[28:29], v[42:43], 1.0 op_sel_hi:[1,0]
	s_waitcnt vmcnt(1)
	v_pk_mul_f32 v[18:19], v[48:49], v[18:19]
	v_pk_mul_f32 v[24:25], v[46:47], v[24:25]
	s_waitcnt vmcnt(0)
	v_pk_mul_f32 v[26:27], v[52:53], v[26:27]
	v_pk_mul_f32 v[28:29], v[50:51], v[28:29]
	v_pk_mul_f32 v[22:23], v[22:23], v[18:19]
	v_pk_mul_f32 v[18:19], v[20:21], v[24:25]
	v_pk_mul_f32 v[24:25], v[36:37], v[26:27]
	v_pk_mul_f32 v[20:21], v[34:35], v[28:29]
	v_cvt_pk_bf16_f32 v18, v18, v19
	v_cvt_pk_bf16_f32 v19, v22, v23
	v_cvt_pk_bf16_f32 v20, v20, v21
	v_cvt_pk_bf16_f32 v21, v24, v25
	v_lshl_add_u64 v[22:23], v[56:57], 1, s[20:21]
	global_store_dwordx4 v[22:23], v[18:21], off
	s_and_saveexec_b64 s[28:29], s[0:1]
	s_cbranch_execz .LBB0_778
	v_lshl_add_u64 v[18:19], v[32:33], 2, s[18:19]
	s_waitcnt lgkmcnt(0)
	v_add_f32_e32 v16, v16, v17
	global_atomic_add_f32 v[18:19], v16, off
.LBB0_778:
	s_or_b64 exec, exec, s[28:29]
	v_add_u32_e32 v16, 0xb0, v146
	s_waitcnt lgkmcnt(0)
	v_ashrrev_i32_e32 v17, 31, v16
	v_lshlrev_b64 v[34:35], 11, v[16:17]
	v_lshl_add_u64 v[36:37], v[34:35], 0, v[148:149]
	v_readlane_b32 s68, v253, 24
	v_lshlrev_b64 v[26:27], 2, v[36:37]
	v_readlane_b32 s69, v253, 25
	global_load_dwordx4 v[18:21], v[144:145], off
	v_lshl_add_u64 v[36:37], v[36:37], 1, s[20:21]
	v_lshl_add_u64 v[38:39], s[68:69], 0, v[26:27]
	global_load_dwordx4 v[22:25], v[38:39], off
	v_lshl_add_u64 v[26:27], s[14:15], 0, v[26:27]
	v_lshl_add_u64 v[40:41], v[34:35], 0, v[124:125]
	v_readlane_b32 s70, v253, 26
	v_readlane_b32 s71, v253, 27
	v_readlane_b32 s72, v253, 28
	v_readlane_b32 s73, v253, 29
	v_readlane_b32 s74, v253, 30
	v_readlane_b32 s75, v253, 31
	v_readlane_b32 s76, v253, 32
	v_readlane_b32 s77, v253, 33
	v_readlane_b32 s78, v253, 34
	v_readlane_b32 s79, v253, 35
	v_readlane_b32 s80, v253, 36
	v_readlane_b32 s81, v253, 37
	v_readlane_b32 s82, v253, 38
	v_readlane_b32 s83, v253, 39
	s_waitcnt vmcnt(0)
	v_pk_fma_f32 v[14:15], v[14:15], v[20:21], v[24:25]
	v_pk_fma_f32 v[12:13], v[12:13], v[18:19], v[22:23]
	global_store_dwordx4 v[26:27], v[12:15], off
	global_load_dwordx4 v[18:21], v[144:145], off offset:16
	global_load_dwordx4 v[22:25], v[38:39], off offset:16
	s_waitcnt vmcnt(0)
	v_pk_fma_f32 v[10:11], v[10:11], v[20:21], v[24:25]
	v_pk_fma_f32 v[8:9], v[8:9], v[18:19], v[22:23]
	global_store_dwordx4 v[26:27], v[8:11], off offset:16
	global_load_dwordx4 v[18:21], v[126:127], off
	global_load_dwordx4 v[22:25], v[126:127], off offset:16
	s_nop 0
	global_load_dwordx4 v[26:29], v[120:121], off
	global_load_dwordx4 v[30:33], v[120:121], off offset:16
	s_waitcnt vmcnt(3)
	v_pk_add_f32 v[20:21], v[20:21], 1.0 op_sel_hi:[1,0]
	v_pk_add_f32 v[18:19], v[18:19], 1.0 op_sel_hi:[1,0]
	s_waitcnt vmcnt(2)
	v_pk_add_f32 v[24:25], v[24:25], 1.0 op_sel_hi:[1,0]
	v_pk_add_f32 v[22:23], v[22:23], 1.0 op_sel_hi:[1,0]
	s_waitcnt vmcnt(1)
	v_pk_mul_f32 v[20:21], v[28:29], v[20:21]
	v_pk_mul_f32 v[18:19], v[26:27], v[18:19]
	s_waitcnt vmcnt(0)
	v_pk_mul_f32 v[24:25], v[32:33], v[24:25]
	v_pk_mul_f32 v[22:23], v[30:31], v[22:23]
	v_pk_mul_f32 v[20:21], v[14:15], v[20:21]
	v_pk_mul_f32 v[18:19], v[12:13], v[18:19]
	v_pk_mul_f32 v[24:25], v[10:11], v[24:25]
	v_pk_mul_f32 v[22:23], v[8:9], v[22:23]
	v_cvt_pk_bf16_f32 v18, v18, v19
	v_cvt_pk_bf16_f32 v19, v20, v21
	v_cvt_pk_bf16_f32 v20, v22, v23
	v_cvt_pk_bf16_f32 v21, v24, v25
	global_store_dwordx4 v[36:37], v[18:21], off
	global_load_dwordx4 v[18:21], v[122:123], off
	s_nop 0
	global_load_dwordx4 v[22:25], v[38:39], off offset:512
	v_lshl_add_u64 v[26:27], v[40:41], 2, s[14:15]
	s_waitcnt vmcnt(0)
	v_pk_fma_f32 v[6:7], v[6:7], v[20:21], v[24:25]
	v_pk_fma_f32 v[4:5], v[4:5], v[18:19], v[22:23]
	global_store_dwordx4 v[26:27], v[4:7], off
	global_load_dwordx4 v[18:21], v[122:123], off offset:16
	global_load_dwordx4 v[22:25], v[38:39], off offset:528
	s_waitcnt vmcnt(0)
	v_pk_fma_f32 v[20:21], v[2:3], v[20:21], v[24:25]
	v_pk_fma_f32 v[18:19], v[0:1], v[18:19], v[22:23]
	global_store_dwordx4 v[26:27], v[18:21], off offset:16
	global_load_dwordx4 v[22:25], v[116:117], off
	s_nop 0
	global_load_dwordx4 v[26:29], v[116:117], off offset:16
	global_load_dwordx4 v[30:33], v[120:121], off offset:512
	global_load_dwordx4 v[34:37], v[120:121], off offset:528
	v_mul_f32_e32 v0, v13, v13
	v_mul_f32_e32 v1, v15, v15
	v_fmac_f32_e32 v0, v12, v12
	v_fmac_f32_e32 v1, v14, v14
	v_add_f32_e32 v0, v0, v1
	v_mul_f32_e32 v1, v9, v9
	v_mul_f32_e32 v2, v11, v11
	v_fmac_f32_e32 v1, v8, v8
	v_fmac_f32_e32 v2, v10, v10
	v_add_f32_e32 v1, v1, v2
	v_add_f32_e32 v0, v0, v1
	v_mul_f32_e32 v1, v5, v5
	v_mul_f32_e32 v2, v7, v7
	v_fmac_f32_e32 v1, v4, v4
	v_fmac_f32_e32 v2, v6, v6
	v_add_f32_e32 v1, v1, v2
	v_add_f32_e32 v0, v0, v1
	v_mul_f32_e32 v1, v19, v19
	v_mul_f32_e32 v2, v21, v21
	v_fmac_f32_e32 v1, v18, v18
	v_fmac_f32_e32 v2, v20, v20
	v_add_f32_e32 v1, v1, v2
	v_add_f32_e32 v0, v0, v1
	ds_bpermute_b32 v1, v114, v0
	s_waitcnt lgkmcnt(0)
	v_add_f32_e32 v0, v0, v1
	ds_bpermute_b32 v1, v115, v0
	s_waitcnt vmcnt(3)
	v_pk_add_f32 v[2:3], v[24:25], 1.0 op_sel_hi:[1,0]
	v_pk_add_f32 v[8:9], v[22:23], 1.0 op_sel_hi:[1,0]
	s_waitcnt vmcnt(2)
	v_pk_add_f32 v[10:11], v[28:29], 1.0 op_sel_hi:[1,0]
	v_pk_add_f32 v[12:13], v[26:27], 1.0 op_sel_hi:[1,0]
	s_waitcnt vmcnt(1)
	v_pk_mul_f32 v[2:3], v[32:33], v[2:3]
	v_pk_mul_f32 v[8:9], v[30:31], v[8:9]
	s_waitcnt vmcnt(0)
	v_pk_mul_f32 v[10:11], v[36:37], v[10:11]
	v_pk_mul_f32 v[12:13], v[34:35], v[12:13]
	v_pk_mul_f32 v[6:7], v[6:7], v[2:3]
	v_pk_mul_f32 v[2:3], v[4:5], v[8:9]
	v_pk_mul_f32 v[8:9], v[20:21], v[10:11]
	v_pk_mul_f32 v[4:5], v[18:19], v[12:13]
	v_cvt_pk_bf16_f32 v2, v2, v3
	v_cvt_pk_bf16_f32 v3, v6, v7
	v_cvt_pk_bf16_f32 v4, v4, v5
	v_cvt_pk_bf16_f32 v5, v8, v9
	v_lshl_add_u64 v[6:7], v[40:41], 1, s[20:21]
	global_store_dwordx4 v[6:7], v[2:5], off
	s_and_saveexec_b64 s[28:29], s[0:1]
	s_cbranch_execz .LBB0_780
	v_lshl_add_u64 v[2:3], v[16:17], 2, s[18:19]
	s_waitcnt lgkmcnt(0)
	v_add_f32_e32 v0, v0, v1
	global_atomic_add_f32 v[2:3], v0, off

.LBB0_943:
	s_ashr_i32 s22, s54, 3
	v_lshl_add_u32 v146, s54, 8, v182
	s_mul_hi_i32 s23, s22, 0xc000
	s_mul_i32 s22, s22, 0xc000
	s_add_u32 s22, s64, s22
	v_lshl_or_b32 v148, s55, 8, v184
	v_ashrrev_i32_e32 v147, 31, v146
	s_addc_u32 s23, s65, s23
	v_lshlrev_b64 v[150:151], 11, v[146:147]
	v_ashrrev_i32_e32 v149, 31, v148
	s_add_u32 s22, s22, 0xa000
	v_lshl_add_u64 v[144:145], v[150:151], 0, v[148:149]
	s_addc_u32 s23, s23, 0
	v_lshl_add_u64 v[152:153], v[144:145], 2, s[14:15]
	v_lshl_add_u64 v[154:155], v[148:149], 2, s[22:23]
	global_load_dwordx4 v[156:159], v[152:153], off
	global_load_dwordx4 v[160:163], v[154:155], off
	v_cndmask_b32_e64 v164, 0, 1, s[62:63]
	v_cmp_ne_u32_e64 s[46:47], 1, v164
	s_andn2_b64 vcc, exec, s[62:63]
	v_lshl_add_u64 v[144:145], v[144:145], 2, s[90:91]
	s_waitcnt vmcnt(0)
	v_pk_fma_f32 v[74:75], v[74:75], v[162:163], v[158:159]
	v_pk_fma_f32 v[72:73], v[72:73], v[160:161], v[156:157]
	s_cbranch_vccnz .LBB0_945
	global_store_dwordx4 v[144:145], v[72:75], off
.LBB0_945:
	global_load_dwordx4 v[156:159], v[152:153], off offset:16
	global_load_dwordx4 v[160:163], v[154:155], off offset:16
	s_and_b64 vcc, exec, s[46:47]
	s_waitcnt vmcnt(0)
	v_pk_fma_f32 v[78:79], v[78:79], v[162:163], v[158:159]
	v_pk_fma_f32 v[76:77], v[76:77], v[160:161], v[156:157]
	s_cbranch_vccnz .LBB0_947
	global_store_dwordx4 v[144:145], v[76:79], off offset:16
.LBB0_947:
	v_or_b32_e32 v162, 0x80, v148
	v_ashrrev_i32_e32 v163, 31, v162
	v_lshl_add_u64 v[150:151], v[150:151], 0, v[162:163]
	v_lshl_add_u64 v[150:151], v[150:151], 2, s[14:15]
	v_lshl_add_u64 v[156:157], v[162:163], 2, s[22:23]
	global_load_dwordx4 v[158:161], v[150:151], off
	global_load_dwordx4 v[164:167], v[156:157], off
	s_and_b64 vcc, exec, s[46:47]
	s_waitcnt vmcnt(0)
	v_pk_fma_f32 v[82:83], v[82:83], v[166:167], v[160:161]
	v_pk_fma_f32 v[80:81], v[80:81], v[164:165], v[158:159]
	s_cbranch_vccnz .LBB0_949
	global_store_dwordx4 v[144:145], v[80:83], off offset:512
.LBB0_949:
	global_load_dwordx4 v[150:153], v[150:151], off offset:16
	s_nop 0
	global_load_dwordx4 v[158:161], v[156:157], off offset:16
	s_and_b64 vcc, exec, s[46:47]
	s_waitcnt vmcnt(0)
	v_pk_fma_f32 v[90:91], v[90:91], v[160:161], v[152:153]
	v_pk_fma_f32 v[88:89], v[88:89], v[158:159], v[150:151]
	s_cbranch_vccnz .LBB0_951
	global_store_dwordx4 v[144:145], v[88:91], off offset:528

.LBB0_953:
	s_or_b64 exec, exec, s[22:23]
	v_or_b32_e32 v150, 16, v146
	s_waitcnt lgkmcnt(0)
	v_ashrrev_i32_e32 v151, 31, v150
	v_lshlrev_b64 v[158:159], 11, v[150:151]
	v_lshl_add_u64 v[152:153], v[158:159], 0, v[148:149]
	v_lshl_add_u64 v[160:161], v[152:153], 2, s[14:15]
	global_load_dwordx4 v[164:167], v[160:161], off
	global_load_dwordx4 v[168:171], v[154:155], off
	s_and_b64 vcc, exec, s[46:47]
	v_lshl_add_u64 v[152:153], v[152:153], 2, s[90:91]
	s_waitcnt vmcnt(0)
	v_pk_fma_f32 v[98:99], v[98:99], v[170:171], v[166:167]
	v_pk_fma_f32 v[96:97], v[96:97], v[168:169], v[164:165]
	s_cbranch_vccnz .LBB0_955
	global_store_dwordx4 v[152:153], v[96:99], off
.LBB0_955:
	global_load_dwordx4 v[164:167], v[160:161], off offset:16
	global_load_dwordx4 v[168:171], v[154:155], off offset:16
	s_and_b64 vcc, exec, s[46:47]
	s_waitcnt vmcnt(0)
	v_pk_fma_f32 v[102:103], v[102:103], v[170:171], v[166:167]
	v_pk_fma_f32 v[100:101], v[100:101], v[168:169], v[164:165]
	s_cbranch_vccnz .LBB0_957
	global_store_dwordx4 v[152:153], v[100:103], off offset:16
.LBB0_957:
	v_lshl_add_u64 v[158:159], v[158:159], 0, v[162:163]
	v_lshl_add_u64 v[158:159], v[158:159], 2, s[14:15]
	global_load_dwordx4 v[164:167], v[158:159], off
	global_load_dwordx4 v[168:171], v[156:157], off
	s_and_b64 vcc, exec, s[46:47]
	s_waitcnt vmcnt(0)
	v_pk_fma_f32 v[110:111], v[110:111], v[170:171], v[166:167]
	v_pk_fma_f32 v[108:109], v[108:109], v[168:169], v[164:165]
	s_cbranch_vccnz .LBB0_959
	global_store_dwordx4 v[152:153], v[108:111], off offset:512
.LBB0_959:
	global_load_dwordx4 v[158:161], v[158:159], off offset:16
	s_nop 0
	global_load_dwordx4 v[164:167], v[156:157], off offset:16
	s_and_b64 vcc, exec, s[46:47]
	s_waitcnt vmcnt(0)
	v_pk_fma_f32 v[114:115], v[114:115], v[166:167], v[160:161]
	v_pk_fma_f32 v[112:113], v[112:113], v[164:165], v[158:159]
	s_cbranch_vccnz .LBB0_961
	global_store_dwordx4 v[152:153], v[112:115], off offset:528

.LBB0_963:
	s_or_b64 exec, exec, s[22:23]
	v_or_b32_e32 v152, 32, v146
	s_waitcnt lgkmcnt(0)
	v_ashrrev_i32_e32 v153, 31, v152
	v_lshlrev_b64 v[164:165], 11, v[152:153]
	v_lshl_add_u64 v[158:159], v[164:165], 0, v[148:149]
	v_lshl_add_u64 v[166:167], v[158:159], 2, s[14:15]
	global_load_dwordx4 v[168:171], v[166:167], off
	global_load_dwordx4 v[172:175], v[154:155], off
	s_and_b64 vcc, exec, s[46:47]
	v_lshl_add_u64 v[158:159], v[158:159], 2, s[90:91]
	s_waitcnt vmcnt(0)
	v_pk_fma_f32 v[122:123], v[122:123], v[174:175], v[170:171]
	v_pk_fma_f32 v[120:121], v[120:121], v[172:173], v[168:169]
	s_cbranch_vccnz .LBB0_965
	global_store_dwordx4 v[158:159], v[120:123], off
.LBB0_965:
	global_load_dwordx4 v[166:169], v[166:167], off offset:16
	s_nop 0
	global_load_dwordx4 v[170:173], v[154:155], off offset:16
	s_and_b64 vcc, exec, s[46:47]
	s_waitcnt vmcnt(0)
	v_pk_fma_f32 v[126:127], v[126:127], v[172:173], v[168:169]
	v_pk_fma_f32 v[124:125], v[124:125], v[170:171], v[166:167]
	s_cbranch_vccnz .LBB0_967
	global_store_dwordx4 v[158:159], v[124:127], off offset:16
.LBB0_967:
	v_lshl_add_u64 v[164:165], v[164:165], 0, v[162:163]
	v_lshl_add_u64 v[164:165], v[164:165], 2, s[14:15]
	global_load_dwordx4 v[166:169], v[164:165], off
	global_load_dwordx4 v[170:173], v[156:157], off
	s_and_b64 vcc, exec, s[46:47]
	s_waitcnt vmcnt(0)
	v_pk_fma_f32 v[118:119], v[118:119], v[172:173], v[168:169]
	v_pk_fma_f32 v[116:117], v[116:117], v[170:171], v[166:167]
	s_cbranch_vccnz .LBB0_969
	global_store_dwordx4 v[158:159], v[116:119], off offset:512
.LBB0_969:
	global_load_dwordx4 v[164:167], v[164:165], off offset:16
	s_nop 0
	global_load_dwordx4 v[168:171], v[156:157], off offset:16
	s_and_b64 vcc, exec, s[46:47]
	s_waitcnt vmcnt(0)
	v_pk_fma_f32 v[106:107], v[106:107], v[170:171], v[166:167]
	v_pk_fma_f32 v[104:105], v[104:105], v[168:169], v[164:165]
	s_cbranch_vccnz .LBB0_971
	global_store_dwordx4 v[158:159], v[104:107], off offset:528

.LBB0_973:
	s_or_b64 exec, exec, s[22:23]
	v_or_b32_e32 v158, 48, v146
	s_waitcnt lgkmcnt(0)
	v_ashrrev_i32_e32 v159, 31, v158
	v_lshlrev_b64 v[168:169], 11, v[158:159]
	v_lshl_add_u64 v[164:165], v[168:169], 0, v[148:149]
	v_lshl_add_u64 v[170:171], v[164:165], 2, s[14:15]
	global_load_dwordx4 v[172:175], v[170:171], off
	global_load_dwordx4 v[176:179], v[154:155], off
	s_and_b64 vcc, exec, s[46:47]
	v_lshl_add_u64 v[164:165], v[164:165], 2, s[90:91]
	s_waitcnt vmcnt(0)
	v_pk_fma_f32 v[94:95], v[94:95], v[178:179], v[174:175]
	v_pk_fma_f32 v[92:93], v[92:93], v[176:177], v[172:173]
	s_cbranch_vccnz .LBB0_975
	global_store_dwordx4 v[164:165], v[92:95], off
.LBB0_975:
	global_load_dwordx4 v[170:173], v[170:171], off offset:16
	s_nop 0
	global_load_dwordx4 v[174:177], v[154:155], off offset:16
	s_and_b64 vcc, exec, s[46:47]
	s_waitcnt vmcnt(0)
	v_pk_fma_f32 v[86:87], v[86:87], v[176:177], v[172:173]
	v_pk_fma_f32 v[84:85], v[84:85], v[174:175], v[170:171]
	s_cbranch_vccnz .LBB0_977
	global_store_dwordx4 v[164:165], v[84:87], off offset:16
.LBB0_977:
	v_lshl_add_u64 v[168:169], v[168:169], 0, v[162:163]
	v_lshl_add_u64 v[168:169], v[168:169], 2, s[14:15]
	global_load_dwordx4 v[170:173], v[168:169], off
	global_load_dwordx4 v[174:177], v[156:157], off
	s_and_b64 vcc, exec, s[46:47]
	s_waitcnt vmcnt(0)
	v_pk_fma_f32 v[70:71], v[70:71], v[176:177], v[172:173]
	v_pk_fma_f32 v[68:69], v[68:69], v[174:175], v[170:171]
	s_cbranch_vccnz .LBB0_979
	global_store_dwordx4 v[164:165], v[68:71], off offset:512
.LBB0_979:
	global_load_dwordx4 v[168:171], v[168:169], off offset:16
	s_nop 0
	global_load_dwordx4 v[172:175], v[156:157], off offset:16
	s_and_b64 vcc, exec, s[46:47]
	s_waitcnt vmcnt(0)
	v_pk_fma_f32 v[66:67], v[66:67], v[174:175], v[170:171]
	v_pk_fma_f32 v[64:65], v[64:65], v[172:173], v[168:169]
	s_cbranch_vccnz .LBB0_981
	global_store_dwordx4 v[164:165], v[64:67], off offset:528

.LBB0_983:
	s_or_b64 exec, exec, s[22:23]
	v_add_u32_e32 v164, 0x80, v146
	s_waitcnt lgkmcnt(0)
	v_ashrrev_i32_e32 v165, 31, v164
	v_lshlrev_b64 v[172:173], 11, v[164:165]
	v_lshl_add_u64 v[168:169], v[172:173], 0, v[148:149]
	v_lshl_add_u64 v[174:175], v[168:169], 2, s[14:15]
	global_load_dwordx4 v[176:179], v[174:175], off
	global_load_dwordx4 v[192:195], v[154:155], off
	s_and_b64 vcc, exec, s[46:47]
	v_lshl_add_u64 v[168:169], v[168:169], 2, s[90:91]
	s_waitcnt vmcnt(0)
	v_pk_fma_f32 v[62:63], v[62:63], v[194:195], v[178:179]
	v_pk_fma_f32 v[60:61], v[60:61], v[192:193], v[176:177]
	s_cbranch_vccnz .LBB0_985
	global_store_dwordx4 v[168:169], v[60:63], off
.LBB0_985:
	global_load_dwordx4 v[174:177], v[174:175], off offset:16
	s_nop 0
	global_load_dwordx4 v[178:181], v[154:155], off offset:16
	s_and_b64 vcc, exec, s[46:47]
	s_waitcnt vmcnt(0)
	v_pk_fma_f32 v[58:59], v[58:59], v[180:181], v[176:177]
	v_pk_fma_f32 v[56:57], v[56:57], v[178:179], v[174:175]
	s_cbranch_vccnz .LBB0_987
	global_store_dwordx4 v[168:169], v[56:59], off offset:16
.LBB0_987:
	v_lshl_add_u64 v[172:173], v[172:173], 0, v[162:163]
	v_lshl_add_u64 v[172:173], v[172:173], 2, s[14:15]
	global_load_dwordx4 v[174:177], v[172:173], off
	global_load_dwordx4 v[178:181], v[156:157], off
	s_and_b64 vcc, exec, s[46:47]
	s_waitcnt vmcnt(0)
	v_pk_fma_f32 v[54:55], v[54:55], v[180:181], v[176:177]
	v_pk_fma_f32 v[52:53], v[52:53], v[178:179], v[174:175]
	s_cbranch_vccnz .LBB0_989
	global_store_dwordx4 v[168:169], v[52:55], off offset:512
.LBB0_989:
	global_load_dwordx4 v[172:175], v[172:173], off offset:16
	s_nop 0
	global_load_dwordx4 v[176:179], v[156:157], off offset:16
	s_and_b64 vcc, exec, s[46:47]
	s_waitcnt vmcnt(0)
	v_pk_fma_f32 v[50:51], v[50:51], v[178:179], v[174:175]
	v_pk_fma_f32 v[48:49], v[48:49], v[176:177], v[172:173]
	s_cbranch_vccnz .LBB0_991
	global_store_dwordx4 v[168:169], v[48:51], off offset:528

.LBB0_993:
	s_or_b64 exec, exec, s[22:23]
	v_add_u32_e32 v168, 0x90, v146
	s_waitcnt lgkmcnt(0)
	v_ashrrev_i32_e32 v169, 31, v168
	v_lshlrev_b64 v[174:175], 11, v[168:169]
	v_lshl_add_u64 v[172:173], v[174:175], 0, v[148:149]
	v_lshl_add_u64 v[176:177], v[172:173], 2, s[14:15]
	global_load_dwordx4 v[178:181], v[176:177], off
	global_load_dwordx4 v[192:195], v[154:155], off
	s_and_b64 vcc, exec, s[46:47]
	v_lshl_add_u64 v[172:173], v[172:173], 2, s[90:91]
	s_waitcnt vmcnt(0)
	v_pk_fma_f32 v[46:47], v[46:47], v[194:195], v[180:181]
	v_pk_fma_f32 v[44:45], v[44:45], v[192:193], v[178:179]
	s_cbranch_vccnz .LBB0_995
	global_store_dwordx4 v[172:173], v[44:47], off
.LBB0_995:
	global_load_dwordx4 v[176:179], v[176:177], off offset:16
	s_nop 0
	global_load_dwordx4 v[192:195], v[154:155], off offset:16
	s_and_b64 vcc, exec, s[46:47]
	s_waitcnt vmcnt(0)
	v_pk_fma_f32 v[42:43], v[42:43], v[194:195], v[178:179]
	v_pk_fma_f32 v[40:41], v[40:41], v[192:193], v[176:177]
	s_cbranch_vccnz .LBB0_997
	global_store_dwordx4 v[172:173], v[40:43], off offset:16
.LBB0_997:
	v_lshl_add_u64 v[174:175], v[174:175], 0, v[162:163]
	v_lshl_add_u64 v[174:175], v[174:175], 2, s[14:15]
	global_load_dwordx4 v[176:179], v[174:175], off
	global_load_dwordx4 v[192:195], v[156:157], off
	s_and_b64 vcc, exec, s[46:47]
	s_waitcnt vmcnt(0)
	v_pk_fma_f32 v[38:39], v[38:39], v[194:195], v[178:179]
	v_pk_fma_f32 v[36:37], v[36:37], v[192:193], v[176:177]
	s_cbranch_vccnz .LBB0_999
	global_store_dwordx4 v[172:173], v[36:39], off offset:512
.LBB0_999:
	global_load_dwordx4 v[174:177], v[174:175], off offset:16
	s_nop 0
	global_load_dwordx4 v[178:181], v[156:157], off offset:16
	s_and_b64 vcc, exec, s[46:47]
	s_waitcnt vmcnt(0)
	v_pk_fma_f32 v[34:35], v[34:35], v[180:181], v[176:177]
	v_pk_fma_f32 v[32:33], v[32:33], v[178:179], v[174:175]
	s_cbranch_vccnz .LBB0_1001
	global_store_dwordx4 v[172:173], v[32:35], off offset:528

.LBB0_1003:
	s_or_b64 exec, exec, s[22:23]
	v_add_u32_e32 v172, 0xa0, v146
	s_waitcnt lgkmcnt(0)
	v_ashrrev_i32_e32 v173, 31, v172
	v_lshlrev_b64 v[176:177], 11, v[172:173]
	v_lshl_add_u64 v[174:175], v[176:177], 0, v[148:149]
	v_lshl_add_u64 v[178:179], v[174:175], 2, s[14:15]
	global_load_dwordx4 v[192:195], v[178:179], off
	global_load_dwordx4 v[196:199], v[154:155], off
	s_and_b64 vcc, exec, s[46:47]
	v_lshl_add_u64 v[174:175], v[174:175], 2, s[90:91]
	s_waitcnt vmcnt(0)
	v_pk_fma_f32 v[30:31], v[30:31], v[198:199], v[194:195]
	v_pk_fma_f32 v[28:29], v[28:29], v[196:197], v[192:193]
	s_cbranch_vccnz .LBB0_1005
	global_store_dwordx4 v[174:175], v[28:31], off
.LBB0_1005:
	global_load_dwordx4 v[178:181], v[178:179], off offset:16
	s_nop 0
	global_load_dwordx4 v[192:195], v[154:155], off offset:16
	s_and_b64 vcc, exec, s[46:47]
	s_waitcnt vmcnt(0)
	v_pk_fma_f32 v[26:27], v[26:27], v[194:195], v[180:181]
	v_pk_fma_f32 v[24:25], v[24:25], v[192:193], v[178:179]
	s_cbranch_vccnz .LBB0_1007
	global_store_dwordx4 v[174:175], v[24:27], off offset:16
.LBB0_1007:
	v_lshl_add_u64 v[176:177], v[176:177], 0, v[162:163]
	v_lshl_add_u64 v[176:177], v[176:177], 2, s[14:15]
	global_load_dwordx4 v[178:181], v[176:177], off
	global_load_dwordx4 v[192:195], v[156:157], off
	s_and_b64 vcc, exec, s[46:47]
	s_waitcnt vmcnt(0)
	v_pk_fma_f32 v[22:23], v[22:23], v[194:195], v[180:181]
	v_pk_fma_f32 v[20:21], v[20:21], v[192:193], v[178:179]
	s_cbranch_vccnz .LBB0_1009
	global_store_dwordx4 v[174:175], v[20:23], off offset:512
.LBB0_1009:
	global_load_dwordx4 v[176:179], v[176:177], off offset:16
	s_nop 0
	global_load_dwordx4 v[192:195], v[156:157], off offset:16
	s_and_b64 vcc, exec, s[46:47]
	s_waitcnt vmcnt(0)
	v_pk_fma_f32 v[18:19], v[18:19], v[194:195], v[178:179]
	v_pk_fma_f32 v[16:17], v[16:17], v[192:193], v[176:177]
	s_cbranch_vccnz .LBB0_1011
	global_store_dwordx4 v[174:175], v[16:19], off offset:528

.LBB0_1013:
	s_or_b64 exec, exec, s[22:23]
	v_add_u32_e32 v174, 0xb0, v146
	s_waitcnt lgkmcnt(0)
	v_ashrrev_i32_e32 v175, 31, v174
	v_lshlrev_b64 v[178:179], 11, v[174:175]
	v_lshl_add_u64 v[176:177], v[178:179], 0, v[148:149]
	v_lshl_add_u64 v[180:181], v[176:177], 2, s[14:15]
	global_load_dwordx4 v[192:195], v[180:181], off
	global_load_dwordx4 v[196:199], v[154:155], off
	s_and_b64 vcc, exec, s[46:47]
	v_lshl_add_u64 v[176:177], v[176:177], 2, s[90:91]
	s_waitcnt vmcnt(0)
	v_pk_fma_f32 v[14:15], v[14:15], v[198:199], v[194:195]
	v_pk_fma_f32 v[12:13], v[12:13], v[196:197], v[192:193]
	s_cbranch_vccnz .LBB0_1015
	global_store_dwordx4 v[176:177], v[12:15], off
.LBB0_1015:
	global_load_dwordx4 v[192:195], v[180:181], off offset:16
	global_load_dwordx4 v[196:199], v[154:155], off offset:16
	s_and_b64 vcc, exec, s[46:47]
	s_waitcnt vmcnt(0)
	v_pk_fma_f32 v[10:11], v[10:11], v[198:199], v[194:195]
	v_pk_fma_f32 v[8:9], v[8:9], v[196:197], v[192:193]
	s_cbranch_vccnz .LBB0_1017
	global_store_dwordx4 v[176:177], v[8:11], off offset:16
.LBB0_1017:
	v_lshl_add_u64 v[154:155], v[178:179], 0, v[162:163]
	v_lshl_add_u64 v[154:155], v[154:155], 2, s[14:15]
	global_load_dwordx4 v[178:181], v[154:155], off
	global_load_dwordx4 v[192:195], v[156:157], off
	s_and_b64 vcc, exec, s[46:47]
	s_waitcnt vmcnt(0)
	v_pk_fma_f32 v[6:7], v[6:7], v[194:195], v[180:181]
	v_pk_fma_f32 v[4:5], v[4:5], v[192:193], v[178:179]
	s_cbranch_vccnz .LBB0_1019
	global_store_dwordx4 v[176:177], v[4:7], off offset:512
.LBB0_1019:
	global_load_dwordx4 v[178:181], v[154:155], off offset:16
	s_nop 0
	global_load_dwordx4 v[154:157], v[156:157], off offset:16
	s_and_b64 vcc, exec, s[46:47]
	s_waitcnt vmcnt(0)
	v_pk_fma_f32 v[2:3], v[2:3], v[156:157], v[180:181]
	v_pk_fma_f32 v[0:1], v[0:1], v[154:155], v[178:179]
	s_cbranch_vccnz .LBB0_1021
	global_store_dwordx4 v[176:177], v[0:3], off offset:528
